# attention steady loops: running reference through the QK^T MFMA C operand (16-register -mhat block) instead of one v_sub per score; rescale branch shifts the block and the pending tile
# baseline (speedup 1.0000x reference)
; #define WAIT_BAR(N) asm volatile("s_waitcnt vmcnt(" #N ") lgkmcnt(0)\n\ts_barrier":::"memory")
;   #define DMA_K(t,slot) glds16(ksrc+(long)(t)*KVBLK*DM,(unsigned)__builtin_amdgcn_readfirstlane(kdst+(slot)))
;   #define DMA_V(t,slot) do{ glds16(vsrc+(long)(t)*KVBLK*DM,(unsigned)__builtin_amdgcn_readfirstlane(vdst+2*(slot))); glds16(vsrc+64+(long)(t)*KVBLK*DM,(unsigned)__builtin_amdgcn_readfirstlane(vdst+2*(slot)+8192)); }while(0)
;   #define CMASK(P0,P1,t) do{int jb_=(t)-(NT-4); if(jb_>=0)cmask(P0,P1,jb_,qrel,hi);}while(0)
;   #define START(P0,P1) do{ const float rm=rowmax(P0,P1); resc=false; mhat=fadd_s(mhat,rm); \
;     _Pragma("unroll") for(int r=0;r<16;++r){P0[r]=fsub_s(P0[r],mhat);P1[r]=fsub_s(P1[r],mhat);} \
;     _Pragma("unroll") for(int r=0;r<16;++r)P0[r]=__builtin_amdgcn_exp2f(P0[r]); }while(0)
;   #define ROT() do{sl_prev=sl_cur;sl_cur=sl_next;sl_next=(sl_next==(NSLOT-1)*SLOTB)?0:sl_next+SLOTB;}while(0)
;   #define CMASK(P0,P1,t) do{}while(0)
;   #define CMASK(P0,P1,t) do{int jb_=(t)-(NT-4); if(jb_>=0)cmask(P0,P1,jb_,qrel,hi);}while(0)
; template<int THRL,int MODE> __device__ __forceinline__ void attn_unit(int b,int qb,const bf16*Q,const bf16*__restrict__ K,const bf16*__restrict__ V,bf16*O,bf16*O2,char*shm,bf16*CM,float lam,const float*gn){
;     ...
;   f32x16 pA0,pA1,pB0,pB1;
;   int sl_prev=0,sl_cur=0,sl_next=SLOTB;
;     ...
;   DMA_K(2,2*SLOTB);
;   WAIT_BAR(4);
;   qkt(pA0,pA1,Kbase,qr,r32,hi);asm volatile("s_nop 15\n\ts_nop 7":"+v"(pA0),"+v"(pA1));CMASK(pA0,pA1,0);
;   START(pA0,pA1);
;   _Pragma("unroll") for(int r=0;r<16;++r)pA1[r]=__builtin_amdgcn_exp2f(pA1[r]);
;   WAIT_BAR(0);
;   DMA_K(3,0);DMA_V(1,SLOTB);
;   ROT();
;   kload8(kf,kp0+sl_cur);
;   WAIT_BAR(3);
;   s16x4 vlo[8],vhi[8]; u32x4 pw0,pw1,pw2,pw3;
.LBB0_1065:
	v_lshlrev_b32_e32 v2, 1, v36
	v_and_b32_e32 v245, 32, v2
	v_lshlrev_b32_e32 v2, 4, v36
	v_and_b32_e32 v2, 0xc0, v2
	v_lshl_or_b32 v243, v214, 8, v2
	v_add_u32_e32 v2, 0, v245
	v_add3_u32 v249, v2, v242, v243
	v_max3_f32 v2, v20, v21, v4
	v_max3_f32 v36, v22, v23, v5
	s_and_b32 s1, s1, 0x3fffffc0
	v_max3_f32 v2, v2, v6, v7
	v_max3_f32 v36, v36, v26, v27
	s_lshl_b32 s1, s1, 2
	v_max3_f32 v2, v2, v24, v25
	v_max3_f32 v36, v36, v10, v11
	s_add_i32 s2, s64, 0x100
	v_max3_f32 v2, v2, v8, v9
	v_max3_f32 v36, v36, v30, v31
	s_add_i32 s66, s1, 0
	v_max3_f32 v2, v2, v28, v29
	v_max3_f32 v36, v36, v14, v15
	s_add_i32 s66, s66, 0x12000
	v_max3_f32 v2, v2, v12, v13
	v_max3_f32 v36, v36, v34, v35
	s_lshr_b32 s63, s2, 6
	v_max3_f32 v2, v2, v32, v33
	v_max3_f32 v36, v36, v18, v19
	s_waitcnt vmcnt(0) lgkmcnt(0)
	s_barrier
	s_cmp_lg_u32 0, -1
	v_max3_f32 v2, v2, v16, v17
	s_mov_b32 s14, 1
	v_max_f32_e32 v2, v2, v36
	s_mov_b32 s1, 0
	v_mov_b32_e32 v36, v2
	s_nop 1
	v_permlane32_swap_b32_e32 v2, v36
	v_max_f32_e32 v2, v2, v36
	v_lshlrev_b32_e32 v250, 4, v214
	v_add_f32_e32 v246, v3, v2
	v_lshl_add_u32 v244, v239, 2, s66
	v_sub_f32_e32 v4, v4, v246
	v_sub_f32_e32 v5, v5, v246
	v_sub_f32_e32 v2, v20, v246
	v_sub_f32_e32 v20, v21, v246
	v_sub_f32_e32 v21, v22, v246
	v_sub_f32_e32 v6, v6, v246
	s_nop 0
	v_exp_f32_e32 v82, v4
	v_exp_f32_e32 v83, v5
	v_lshl_add_u64 v[4:5], v[224:225], 0, s[22:23]
	s_mov_b32 s2, m0
	s_mov_b32 m0, s67
	s_nop 0
	global_load_lds_dwordx4 v[4:5], off
	s_mov_b32 m0, s2
	s_cselect_b32 s2, 0, 0
	s_add_i32 s0, s2, s0
	v_lshl_add_u64 v[4:5], v[226:227], 0, s[18:19]
	s_add_i32 s2, s0, 0xa000
	s_mov_b32 s6, m0
	s_mov_b32 m0, s2
	s_nop 0
	global_load_lds_dwordx4 v[4:5], off
	s_mov_b32 m0, s6
	v_lshl_add_u64 v[4:5], v[226:227], 0, s[24:25]
	s_add_i32 s0, s0, 0xc000
	s_mov_b32 s2, m0
	s_mov_b32 m0, s0
	s_nop 0
	global_load_lds_dwordx4 v[4:5], off
	s_mov_b32 m0, s2
	ds_read_b128 v[206:209], v248 offset:8192
	ds_read_b128 v[202:205], v248 offset:8704
	ds_read_b128 v[198:201], v248 offset:10240
	ds_read_b128 v[194:197], v248 offset:10752
	ds_read_b128 v[190:193], v248 offset:12288
	ds_read_b128 v[186:189], v248 offset:12800
	ds_read_b128 v[182:185], v248 offset:14336
	ds_read_b128 v[178:181], v248 offset:14848
	v_sub_f32_e32 v22, v23, v246
	v_sub_f32_e32 v7, v7, v246
	v_sub_f32_e32 v23, v24, v246
	v_sub_f32_e32 v8, v8, v246
	v_sub_f32_e32 v24, v25, v246
	v_sub_f32_e32 v9, v9, v246
	v_sub_f32_e32 v25, v26, v246
	v_sub_f32_e32 v10, v10, v246
	v_sub_f32_e32 v26, v27, v246
	v_sub_f32_e32 v11, v11, v246
	v_sub_f32_e32 v27, v28, v246
	v_sub_f32_e32 v12, v12, v246
	v_sub_f32_e32 v28, v29, v246
	v_sub_f32_e32 v13, v13, v246
	v_sub_f32_e32 v29, v30, v246
	v_sub_f32_e32 v14, v14, v246
	v_sub_f32_e32 v30, v31, v246
	v_sub_f32_e32 v15, v15, v246
	v_sub_f32_e32 v31, v32, v246
	v_sub_f32_e32 v16, v16, v246
	v_sub_f32_e32 v32, v33, v246
	v_sub_f32_e32 v17, v17, v246
	v_sub_f32_e32 v33, v34, v246
	v_sub_f32_e32 v18, v18, v246
	v_sub_f32_e32 v34, v35, v246
	v_sub_f32_e32 v19, v19, v246
	v_exp_f32_e32 v98, v2
	v_exp_f32_e32 v99, v20
	v_exp_f32_e32 v100, v21
	v_exp_f32_e32 v101, v22
	v_exp_f32_e32 v102, v23
	v_exp_f32_e32 v103, v24
	v_exp_f32_e32 v104, v25
	v_exp_f32_e32 v105, v26
	v_exp_f32_e32 v106, v27
	v_exp_f32_e32 v107, v28
	v_exp_f32_e32 v108, v29
	v_exp_f32_e32 v109, v30
	v_exp_f32_e32 v110, v31
	v_exp_f32_e32 v111, v32
	v_exp_f32_e32 v112, v33
	v_exp_f32_e32 v113, v34
	v_exp_f32_e32 v84, v6
	v_exp_f32_e32 v85, v7
	v_exp_f32_e32 v86, v8
	v_exp_f32_e32 v87, v9
	v_exp_f32_e32 v88, v10
	v_exp_f32_e32 v89, v11
	v_exp_f32_e32 v90, v12
	v_exp_f32_e32 v91, v13
	v_exp_f32_e32 v92, v14
	v_exp_f32_e32 v93, v15
	v_exp_f32_e32 v94, v16
	v_exp_f32_e32 v95, v17
	v_exp_f32_e32 v96, v18
	v_exp_f32_e32 v97, v19
	s_waitcnt vmcnt(3) lgkmcnt(0)
	s_barrier
	v_cndmask_b32_e64 v2, 0, 1, s[8:9]
	v_cmp_ne_u32_e64 s[6:7], 1, v2
	s_andn2_b64 vcc, exec, s[8:9]
	v_cmp_gt_u32_e64 s[8:9], 32, v238
	s_cbranch_vccnz .LBB0_1081
	v_mov_b32_e32 v16, v3
	v_mov_b32_e32 v17, v3
	v_mov_b32_e32 v2, v3
	v_mov_b32_e32 v4, v3
	v_mov_b32_e32 v5, v3
	v_mov_b32_e32 v6, v3
	v_mov_b32_e32 v7, v3
	v_mov_b32_e32 v8, v3
	v_mov_b32_e32 v9, v3
	v_mov_b32_e32 v10, v3
	v_mov_b32_e32 v11, v3
	v_mov_b32_e32 v12, v3
	v_mov_b32_e32 v13, v3
	v_mov_b32_e32 v14, v3
	v_mov_b32_e32 v15, v3
	v_mov_b64_e32 v[80:81], v[16:17]
	v_mov_b64_e32 v[64:65], v[16:17]
	v_mov_b64_e32 v[48:49], v[16:17]
	v_mov_b64_e32 v[32:33], v[16:17]
	s_mov_b32 s33, 0
	s_movk_i32 s1, 0x4000
	s_movk_i32 s14, 0x2000
	v_mov_b32_e32 v251, 0
	s_mov_b32 s2, 6
	s_mov_b64 s[38:39], 0
	v_mov_b64_e32 v[78:79], v[14:15]
	v_mov_b64_e32 v[76:77], v[12:13]
	v_mov_b64_e32 v[74:75], v[10:11]
	v_mov_b64_e32 v[72:73], v[8:9]
	v_mov_b64_e32 v[70:71], v[6:7]
	v_mov_b64_e32 v[68:69], v[4:5]
	v_mov_b64_e32 v[66:67], v[2:3]
	v_mov_b64_e32 v[62:63], v[14:15]
	v_mov_b64_e32 v[60:61], v[12:13]
	v_mov_b64_e32 v[58:59], v[10:11]
	v_mov_b64_e32 v[56:57], v[8:9]
	v_mov_b64_e32 v[54:55], v[6:7]
	v_mov_b64_e32 v[52:53], v[4:5]
	v_mov_b64_e32 v[50:51], v[2:3]
	v_mov_b64_e32 v[46:47], v[14:15]
	v_mov_b64_e32 v[44:45], v[12:13]
	v_mov_b64_e32 v[42:43], v[10:11]
	v_mov_b64_e32 v[40:41], v[8:9]
	v_mov_b64_e32 v[38:39], v[6:7]
	v_mov_b64_e32 v[36:37], v[4:5]
	v_mov_b64_e32 v[34:35], v[2:3]
	v_mov_b64_e32 v[30:31], v[14:15]
	v_mov_b64_e32 v[28:29], v[12:13]
	v_mov_b64_e32 v[26:27], v[10:11]
	v_mov_b64_e32 v[24:25], v[8:9]
	v_mov_b64_e32 v[22:23], v[6:7]
	v_mov_b64_e32 v[20:21], v[4:5]
	v_mov_b64_e32 v[18:19], v[2:3]
	v_readfirstlane_b32 s98, v222
	v_readfirstlane_b32 s99, v223
	v_mov_b32_e32 v216, v224
	v_mov_b32_e32 v217, v225
	v_mov_b32_e32 v252, v226
	v_mov_b32_e32 v253, v227
	v_sub_f32_e32 v218, 0, v246
	v_sub_f32_e32 v219, 0, v246
	v_sub_f32_e32 v220, 0, v246
	v_sub_f32_e32 v221, 0, v246
	v_sub_f32_e32 v222, 0, v246
	v_sub_f32_e32 v223, 0, v246
	v_sub_f32_e32 v224, 0, v246
	v_sub_f32_e32 v225, 0, v246
	v_sub_f32_e32 v226, 0, v246
	v_sub_f32_e32 v227, 0, v246
	v_sub_f32_e32 v228, 0, v246
	v_sub_f32_e32 v229, 0, v246
	v_sub_f32_e32 v230, 0, v246
	v_sub_f32_e32 v231, 0, v246
	v_sub_f32_e32 v232, 0, v246
	v_sub_f32_e32 v233, 0, v246
	s_nop 1
.LBB0_1067:
	s_lshl_b32 s0, s33, 1
	v_add_u32_e32 v2, s0, v249
	ds_read_b64_tr_b16 v[210:211], v2 offset:24576
	ds_read_b64_tr_b16 v[212:213], v2 offset:25088
	s_waitcnt lgkmcnt(9)
	v_mfma_f32_32x32x16_bf16 v[130:145], v[206:209], v[174:177], v[218:233]
	v_add_f32_e32 v4, v98, v99
	v_add_f32_e32 v4, v100, v4
	v_add_f32_e32 v4, v101, v4
	v_add_f32_e32 v4, v102, v4
	v_add_f32_e32 v4, v103, v4
	v_cvt_pk_bf16_f32 v170, v98, v99
	v_cvt_pk_bf16_f32 v171, v100, v101
	ds_read_b64_tr_b16 v[206:207], v2 offset:28672
	ds_read_b64_tr_b16 v[208:209], v2 offset:29184
	s_waitcnt lgkmcnt(10)
	v_mfma_f32_32x32x16_bf16 v[114:129], v[202:205], v[174:177], v[218:233]
	v_add_f32_e32 v4, v104, v4
	v_add_f32_e32 v4, v105, v4
	v_add_f32_e32 v4, v106, v4
	v_add_f32_e32 v4, v107, v4
	v_cvt_pk_bf16_f32 v172, v102, v103
	v_cvt_pk_bf16_f32 v173, v104, v105
	ds_read_b64_tr_b16 v[12:13], v2 offset:25600
	ds_read_b64_tr_b16 v[14:15], v2 offset:26112
	s_waitcnt lgkmcnt(11)
	v_mfma_f32_32x32x16_bf16 v[130:145], v[198:201], v[166:169], v[130:145]
	v_add_f32_e32 v4, v108, v4
	v_add_f32_e32 v4, v109, v4
	v_add_f32_e32 v4, v110, v4
	v_add_f32_e32 v4, v111, v4
	v_cvt_pk_bf16_f32 v162, v106, v107
	v_cvt_pk_bf16_f32 v163, v108, v109
	ds_read_b64_tr_b16 v[8:9], v2 offset:29696
	ds_read_b64_tr_b16 v[10:11], v2 offset:30208
	s_waitcnt lgkmcnt(12)
	v_mfma_f32_32x32x16_bf16 v[114:129], v[194:197], v[166:169], v[114:129]
	v_add_f32_e32 v4, v112, v4
	v_add_f32_e32 v4, v113, v4
	v_add_f32_e32 v4, v82, v4
	v_add_f32_e32 v16, v83, v4
	v_cvt_pk_bf16_f32 v164, v110, v111
	v_cvt_pk_bf16_f32 v165, v112, v113
	ds_read_b64_tr_b16 v[4:5], v2 offset:26624
	ds_read_b64_tr_b16 v[6:7], v2 offset:27136
	s_waitcnt lgkmcnt(13)
	v_mfma_f32_32x32x16_bf16 v[130:145], v[190:193], v[158:161], v[130:145]
	v_add_f32_e32 v16, v84, v16
	v_add_f32_e32 v16, v85, v16
	v_add_f32_e32 v16, v86, v16
	v_add_f32_e32 v16, v87, v16
	v_cvt_pk_bf16_f32 v154, v82, v83
	v_cvt_pk_bf16_f32 v155, v84, v85
	ds_read_b64_tr_b16 v[102:103], v2 offset:30720
	ds_read_b64_tr_b16 v[104:105], v2 offset:31232
	s_waitcnt lgkmcnt(14)
	v_mfma_f32_32x32x16_bf16 v[114:129], v[186:189], v[158:161], v[114:129]
	v_add_f32_e32 v16, v88, v16
	v_add_f32_e32 v16, v89, v16
	v_add_f32_e32 v16, v90, v16
	v_add_f32_e32 v16, v91, v16
	v_cvt_pk_bf16_f32 v156, v86, v87
	v_cvt_pk_bf16_f32 v157, v88, v89
	ds_read_b64_tr_b16 v[98:99], v2 offset:27648
	ds_read_b64_tr_b16 v[100:101], v2 offset:28160
	s_waitcnt lgkmcnt(14)
	v_mfma_f32_32x32x16_bf16 v[130:145], v[182:185], v[150:153], v[130:145]
	v_add_f32_e32 v16, v92, v16
	v_add_f32_e32 v16, v93, v16
	v_add_f32_e32 v16, v94, v16
	v_add_f32_e32 v16, v95, v16
	v_cvt_pk_bf16_f32 v146, v90, v91
	v_cvt_pk_bf16_f32 v147, v92, v93
	ds_read_b64_tr_b16 v[90:91], v2 offset:31744
	ds_read_b64_tr_b16 v[92:93], v2 offset:32256
	v_mfma_f32_32x32x16_bf16 v[114:129], v[178:181], v[150:153], v[114:129]
	v_add_f32_e32 v16, v96, v16
	v_add_f32_e32 v16, v97, v16
	v_add_f32_e32 v84, 0, v16
	v_cvt_pk_bf16_f32 v148, v94, v95
	v_cvt_pk_bf16_f32 v149, v96, v97
	v_lshl_add_u64 v[16:17], v[216:217], 0, s[38:39]
	v_lshl_add_u64 v[82:83], v[16:17], 0, s[26:27]
	s_add_i32 s0, s14, s67
	v_lshl_add_u64 v[202:203], v[252:253], 0, s[38:39]
	s_mov_b32 s33, m0
	s_mov_b32 m0, s0
	s_nop 0
	global_load_lds_dwordx4 v[82:83], off
	s_mov_b32 m0, s33
	v_lshl_add_u64 v[82:83], v[202:203], 0, s[20:21]
	s_lshl_b32 s0, s1, 1
	v_lshl_add_u64 v[204:205], v[202:203], 0, s[16:17]
	s_add_i32 s0, s0, s68
	s_mov_b32 s33, m0
	s_mov_b32 m0, s0
	s_nop 0
	global_load_lds_dwordx4 v[82:83], off
	s_mov_b32 m0, s33
	v_lshl_add_u64 v[82:83], v[204:205], 0, s[20:21]
	s_addk_i32 s0, 0x2000
	s_mov_b32 s33, m0
	s_mov_b32 m0, s0
	s_nop 0
	global_load_lds_dwordx4 v[82:83], off
	s_mov_b32 m0, s33
	v_max_f32_e32 v82, v131, v131
	v_max_f32_e32 v83, v130, v130
	v_max_f32_e32 v82, v83, v82
	v_max3_f32 v83, v132, v133, v115
	v_max3_f32 v82, v82, v114, v116
	v_max3_f32 v82, v82, v117, v134
	v_max3_f32 v83, v83, v136, v137
	v_max3_f32 v82, v82, v135, v118
	v_max3_f32 v83, v83, v120, v121
	v_max3_f32 v82, v82, v119, v138
	v_max3_f32 v83, v83, v140, v141
	v_max3_f32 v82, v82, v139, v122
	v_max3_f32 v83, v83, v124, v125
	v_max3_f32 v82, v82, v123, v142
	v_max3_f32 v83, v83, v144, v145
	v_max3_f32 v82, v82, v143, v126
	v_max3_f32 v83, v83, v128, v129
	v_max3_f32 v82, v82, v127, v83
	v_mov_b32_e32 v83, v82
	s_nop 1
	v_permlane32_swap_b32_e32 v82, v83
	v_max_f32_e32 v83, v83, v83
	v_max_f32_e32 v82, v82, v82
	v_max_f32_e32 v82, v82, v83
	v_cmp_lt_f32_e32 vcc, s55, v82
	s_cmp_lg_u64 vcc, 0
	v_add_f32_e32 v215, v251, v84
	s_cselect_b64 s[40:41], -1, 0
	s_cbranch_vccnz .LBB0_1075
; #define WAIT_BAR(N) asm volatile("s_waitcnt vmcnt(" #N ") lgkmcnt(0)\n\ts_barrier":::"memory")
;   #define RESC() do{ if(resc){ asm volatile("s_waitcnt lgkmcnt(0)":::"memory"); \
;       _Pragma("unroll") for(int d_=0;d_<4;++d_) _Pragma("unroll") for(int r=0;r<16;++r)o[d_][r]*=wsf[crow(r,hi)]; } }while(0)
;   #define ROT() do{sl_prev=sl_cur;sl_cur=sl_next;sl_next=(sl_next==(NSLOT-1)*SLOTB)?0:sl_next+SLOTB;}while(0)
; template<int THRL,int MODE> __device__ __forceinline__ void attn_unit(int b,int qb,const bf16*Q,const bf16*__restrict__ K,const bf16*__restrict__ V,bf16*O,bf16*O2,char*shm,bf16*CM,float lam,const float*gn){
;     ...
;   int t=1;
;     ...
;   for(;t+5<NT;t+=2){
;     STEP(pB0,pB1,pA0,pA1,t,true,true,true);     WAIT_BAR(3); RESC(); ROT();
.LBB0_1068:
	s_waitcnt lgkmcnt(14)
	v_mfma_f32_32x32x16_bf16 v[66:81], v[170:173], v[210:213], v[66:81]
	v_exp_f32_e32 v130, v130
	v_exp_f32_e32 v131, v131
	ds_read_b64_tr_b16 v[94:95], v2 offset:32768
	ds_read_b64_tr_b16 v[96:97], v2 offset:33280
	s_waitcnt lgkmcnt(14)
	v_mfma_f32_32x32x16_bf16 v[50:65], v[170:173], v[206:209], v[50:65]
	v_exp_f32_e32 v132, v132
	v_exp_f32_e32 v133, v133
	ds_read_b64_tr_b16 v[106:107], v2 offset:36864
	ds_read_b64_tr_b16 v[108:109], v2 offset:37376
	v_add_u32_e32 v198, s1, v248
	ds_read_b128 v[86:89], v198
	ds_read_b128 v[82:85], v198 offset:512
	s_waitcnt lgkmcnt(14)
	v_mfma_f32_32x32x16_bf16 v[66:81], v[162:165], v[12:15], v[66:81]
	v_exp_f32_e32 v134, v134
	v_exp_f32_e32 v135, v135
	ds_read_b64_tr_b16 v[110:111], v2 offset:33792
	ds_read_b64_tr_b16 v[112:113], v2 offset:34304
	ds_read_b128 v[186:189], v198 offset:2048
	ds_read_b128 v[178:181], v198 offset:2560
	v_mfma_f32_32x32x16_bf16 v[50:65], v[162:165], v[8:11], v[50:65]
	v_exp_f32_e32 v136, v136
	v_exp_f32_e32 v137, v137
	ds_read_b64_tr_b16 v[190:191], v2 offset:37888
	ds_read_b64_tr_b16 v[192:193], v2 offset:38400
	ds_read_b128 v[182:185], v198 offset:4096
	ds_read_b128 v[8:11], v198 offset:4608
	s_waitcnt lgkmcnt(14)
	v_mfma_f32_32x32x16_bf16 v[66:81], v[154:157], v[4:7], v[66:81]
	v_exp_f32_e32 v138, v138
	v_exp_f32_e32 v139, v139
	ds_read_b64_tr_b16 v[194:195], v2 offset:34816
	ds_read_b64_tr_b16 v[196:197], v2 offset:35328
	ds_read_b128 v[12:15], v198 offset:6144
	ds_read_b128 v[4:7], v198 offset:6656
	v_mfma_f32_32x32x16_bf16 v[50:65], v[154:157], v[102:105], v[50:65]
	v_exp_f32_e32 v140, v140
	v_exp_f32_e32 v141, v141
	ds_read_b64_tr_b16 v[102:103], v2 offset:38912
	ds_read_b64_tr_b16 v[104:105], v2 offset:39424
	v_mfma_f32_32x32x16_bf16 v[66:81], v[146:149], v[98:101], v[66:81]
	v_exp_f32_e32 v142, v142
	v_exp_f32_e32 v143, v143
	ds_read_b64_tr_b16 v[98:99], v2 offset:35840
	ds_read_b64_tr_b16 v[100:101], v2 offset:36352
	v_mfma_f32_32x32x16_bf16 v[50:65], v[146:149], v[90:93], v[50:65]
	v_exp_f32_e32 v144, v144
	v_exp_f32_e32 v145, v145
	ds_read_b64_tr_b16 v[90:91], v2 offset:39936
	ds_read_b64_tr_b16 v[92:93], v2 offset:40448
	s_waitcnt lgkmcnt(14)
	v_mfma_f32_32x32x16_bf16 v[34:49], v[170:173], v[94:97], v[34:49]
	v_exp_f32_e32 v114, v114
	v_exp_f32_e32 v115, v115
	v_mfma_f32_32x32x16_bf16 v[18:33], v[170:173], v[106:109], v[18:33]
	v_exp_f32_e32 v116, v116
	v_exp_f32_e32 v117, v117
	v_mfma_f32_32x32x16_bf16 v[34:49], v[162:165], v[110:113], v[34:49]
	v_exp_f32_e32 v118, v118
	v_exp_f32_e32 v119, v119
	s_waitcnt lgkmcnt(12)
	v_mfma_f32_32x32x16_bf16 v[18:33], v[162:165], v[190:193], v[18:33]
	v_exp_f32_e32 v120, v120
	v_exp_f32_e32 v121, v121
	s_waitcnt lgkmcnt(8)
	v_mfma_f32_32x32x16_bf16 v[34:49], v[154:157], v[194:197], v[34:49]
	v_exp_f32_e32 v122, v122
	v_exp_f32_e32 v123, v123
	s_waitcnt lgkmcnt(4)
	v_mfma_f32_32x32x16_bf16 v[18:33], v[154:157], v[102:105], v[18:33]
	v_exp_f32_e32 v124, v124
	v_exp_f32_e32 v125, v125
	s_waitcnt lgkmcnt(2)
	v_mfma_f32_32x32x16_bf16 v[34:49], v[146:149], v[98:101], v[34:49]
	v_exp_f32_e32 v126, v126
	v_exp_f32_e32 v127, v127
	s_waitcnt lgkmcnt(0)
	v_mfma_f32_32x32x16_bf16 v[18:33], v[146:149], v[90:93], v[18:33]
	v_exp_f32_e32 v128, v128
	v_exp_f32_e32 v129, v129
	s_waitcnt vmcnt(3) lgkmcnt(0)
	s_barrier
	s_andn2_b64 vcc, exec, s[40:41]
	v_add_u32_e32 v2, s66, v250
	s_cbranch_vccnz .LBB0_1070
	s_waitcnt lgkmcnt(0)
	ds_read_b128 v[90:93], v2 offset:96
	ds_read_b128 v[94:97], v2 offset:64
	ds_read_b128 v[98:101], v2 offset:32
	ds_read_b128 v[102:105], v2
	s_waitcnt lgkmcnt(3)
	v_pk_mul_f32 v[78:79], v[78:79], v[90:91]
	s_waitcnt lgkmcnt(2)
	v_pk_mul_f32 v[74:75], v[74:75], v[94:95]
	s_waitcnt lgkmcnt(1)
	v_pk_mul_f32 v[70:71], v[70:71], v[98:99]
	v_pk_mul_f32 v[80:81], v[80:81], v[92:93]
	v_pk_mul_f32 v[76:77], v[76:77], v[96:97]
	v_pk_mul_f32 v[72:73], v[72:73], v[100:101]
	s_waitcnt lgkmcnt(0)
	v_pk_mul_f32 v[68:69], v[68:69], v[104:105]
	v_pk_mul_f32 v[66:67], v[66:67], v[102:103]
	v_pk_mul_f32 v[62:63], v[62:63], v[90:91]
	v_pk_mul_f32 v[58:59], v[58:59], v[94:95]
	v_pk_mul_f32 v[54:55], v[54:55], v[98:99]
	v_pk_mul_f32 v[64:65], v[64:65], v[92:93]
	v_pk_mul_f32 v[60:61], v[60:61], v[96:97]
	v_pk_mul_f32 v[56:57], v[56:57], v[100:101]
	v_pk_mul_f32 v[52:53], v[52:53], v[104:105]
	v_pk_mul_f32 v[50:51], v[50:51], v[102:103]
	v_pk_mul_f32 v[46:47], v[46:47], v[90:91]
	v_pk_mul_f32 v[42:43], v[42:43], v[94:95]
	v_pk_mul_f32 v[38:39], v[38:39], v[98:99]
	v_pk_mul_f32 v[48:49], v[48:49], v[92:93]
	v_pk_mul_f32 v[44:45], v[44:45], v[96:97]
	v_pk_mul_f32 v[40:41], v[40:41], v[100:101]
	v_pk_mul_f32 v[36:37], v[36:37], v[104:105]
	v_pk_mul_f32 v[34:35], v[34:35], v[102:103]
	v_pk_mul_f32 v[30:31], v[30:31], v[90:91]
	v_pk_mul_f32 v[26:27], v[26:27], v[94:95]
	v_pk_mul_f32 v[22:23], v[22:23], v[98:99]
	v_pk_mul_f32 v[32:33], v[32:33], v[92:93]
	v_pk_mul_f32 v[28:29], v[28:29], v[96:97]
	v_pk_mul_f32 v[24:25], v[24:25], v[100:101]
	v_pk_mul_f32 v[20:21], v[20:21], v[104:105]
	v_pk_mul_f32 v[18:19], v[18:19], v[102:103]
.LBB0_1070:
	s_add_i32 s0, s1, 0x2000
	s_cmpk_lg_i32 s1, 0x4000
	s_cselect_b32 s69, s0, 0
	s_lshl_b32 s0, s14, 1
	v_add_u32_e32 v210, s0, v249
	ds_read_b64_tr_b16 v[198:199], v210 offset:24576
	ds_read_b64_tr_b16 v[200:201], v210 offset:25088
	v_mfma_f32_32x32x16_bf16 v[98:113], v[86:89], v[174:177], v[218:233]
	v_add_f32_e32 v90, v130, v131
	v_add_f32_e32 v90, v132, v90
	v_add_f32_e32 v90, v133, v90
	v_add_f32_e32 v90, v134, v90
	v_add_f32_e32 v90, v135, v90
	v_cvt_pk_bf16_f32 v170, v130, v131
	v_cvt_pk_bf16_f32 v171, v132, v133
	ds_read_b64_tr_b16 v[194:195], v210 offset:28672
	ds_read_b64_tr_b16 v[196:197], v210 offset:29184
	v_add_f32_e32 v86, v136, v90
	v_add_f32_e32 v86, v137, v86
	v_add_f32_e32 v86, v138, v86
	v_add_f32_e32 v130, v139, v86
	v_mfma_f32_32x32x16_bf16 v[82:97], v[82:85], v[174:177], v[218:233]
	v_cvt_pk_bf16_f32 v172, v134, v135
	v_cvt_pk_bf16_f32 v173, v136, v137
	ds_read_b64_tr_b16 v[190:191], v210 offset:25600
	ds_read_b64_tr_b16 v[192:193], v210 offset:26112
	v_mfma_f32_32x32x16_bf16 v[98:113], v[186:189], v[166:169], v[98:113]
	v_add_f32_e32 v130, v140, v130
	v_add_f32_e32 v130, v141, v130
	v_add_f32_e32 v130, v142, v130
	v_add_f32_e32 v130, v143, v130
	v_cvt_pk_bf16_f32 v162, v138, v139
	v_cvt_pk_bf16_f32 v163, v140, v141
	ds_read_b64_tr_b16 v[138:139], v210 offset:29696
	ds_read_b64_tr_b16 v[140:141], v210 offset:30208
	v_mfma_f32_32x32x16_bf16 v[82:97], v[178:181], v[166:169], v[82:97]
	v_add_f32_e32 v130, v144, v130
	v_add_f32_e32 v130, v145, v130
	v_add_f32_e32 v130, v114, v130
	v_add_f32_e32 v130, v115, v130
	v_cvt_pk_bf16_f32 v164, v142, v143
	v_cvt_pk_bf16_f32 v165, v144, v145
	ds_read_b64_tr_b16 v[134:135], v210 offset:26624
	ds_read_b64_tr_b16 v[136:137], v210 offset:27136
	v_mfma_f32_32x32x16_bf16 v[98:113], v[182:185], v[158:161], v[98:113]
	v_add_f32_e32 v130, v116, v130
	v_add_f32_e32 v130, v117, v130
	v_add_f32_e32 v130, v118, v130
	v_add_f32_e32 v142, v119, v130
	v_cvt_pk_bf16_f32 v154, v114, v115
	v_cvt_pk_bf16_f32 v155, v116, v117
	ds_read_b64_tr_b16 v[130:131], v210 offset:30720
	ds_read_b64_tr_b16 v[132:133], v210 offset:31232
	v_mfma_f32_32x32x16_bf16 v[82:97], v[8:11], v[158:161], v[82:97]
	v_add_f32_e32 v114, v120, v142
	v_add_f32_e32 v114, v121, v114
	v_add_f32_e32 v114, v122, v114
	v_add_f32_e32 v142, v123, v114
	v_cvt_pk_bf16_f32 v156, v118, v119
	v_cvt_pk_bf16_f32 v157, v120, v121
	ds_read_b64_tr_b16 v[114:115], v210 offset:27648
	ds_read_b64_tr_b16 v[116:117], v210 offset:28160
	v_mfma_f32_32x32x16_bf16 v[98:113], v[12:15], v[150:153], v[98:113]
	v_add_f32_e32 v8, v124, v142
	v_add_f32_e32 v8, v125, v8
	v_add_f32_e32 v8, v126, v8
	v_add_f32_e32 v118, v127, v8
	v_cvt_pk_bf16_f32 v146, v122, v123
	v_cvt_pk_bf16_f32 v147, v124, v125
	ds_read_b64_tr_b16 v[8:9], v210 offset:31744
	ds_read_b64_tr_b16 v[10:11], v210 offset:32256
	v_mfma_f32_32x32x16_bf16 v[82:97], v[4:7], v[150:153], v[82:97]
	v_add_f32_e32 v12, v128, v118
	v_add_f32_e32 v12, v129, v12
	v_add_f32_e32 v12, 0, v12
	v_cvt_pk_bf16_f32 v148, v126, v127
	v_cvt_pk_bf16_f32 v149, v128, v129
	v_lshl_add_u64 v[4:5], v[16:17], 0, s[28:29]
	s_add_i32 s0, s1, s67
	s_mov_b32 s14, m0
	s_mov_b32 m0, s0
	s_nop 0
	global_load_lds_dwordx4 v[4:5], off
	s_mov_b32 m0, s14
	v_lshl_add_u64 v[4:5], v[202:203], 0, s[22:23]
	s_lshl_b32 s0, s69, 1
	s_add_i32 s0, s0, s68
	s_mov_b32 s14, m0
	s_mov_b32 m0, s0
	s_nop 0
	global_load_lds_dwordx4 v[4:5], off
	s_mov_b32 m0, s14
	v_lshl_add_u64 v[4:5], v[204:205], 0, s[22:23]
	s_addk_i32 s0, 0x2000
	s_mov_b32 s14, m0
	s_mov_b32 m0, s0
	s_nop 0
	global_load_lds_dwordx4 v[4:5], off
	s_mov_b32 m0, s14
	v_max_f32_e32 v4, v99, v99
	v_max_f32_e32 v5, v98, v98
	v_max_f32_e32 v4, v5, v4
	v_max3_f32 v5, v100, v101, v83
	v_max3_f32 v4, v4, v82, v84
	v_max3_f32 v4, v4, v85, v102
	v_max3_f32 v5, v5, v104, v105
	v_max3_f32 v4, v4, v103, v86
	v_max3_f32 v5, v5, v88, v89
	v_max3_f32 v4, v4, v87, v106
	v_max3_f32 v5, v5, v108, v109
	v_max3_f32 v4, v4, v107, v90
	v_max3_f32 v5, v5, v92, v93
	v_max3_f32 v4, v4, v91, v110
	v_max3_f32 v5, v5, v112, v113
	v_max3_f32 v4, v4, v111, v94
	v_max3_f32 v5, v5, v96, v97
	v_max3_f32 v4, v4, v95, v5
	v_mov_b32_e32 v5, v4
	s_nop 1
	v_permlane32_swap_b32_e32 v4, v5
	v_max_f32_e32 v5, v5, v5
	v_max_f32_e32 v4, v4, v4
	v_max_f32_e32 v4, v4, v5
	v_cmp_lt_f32_e32 vcc, s55, v4
	s_cmp_lg_u64 vcc, 0
	v_add_f32_e32 v251, v215, v12
	s_cselect_b64 s[40:41], -1, 0
	s_cbranch_vccnz .LBB0_1078
; #define WAIT_BAR(N) asm volatile("s_waitcnt vmcnt(" #N ") lgkmcnt(0)\n\ts_barrier":::"memory")
;   #define RESC() do{ if(resc){ asm volatile("s_waitcnt lgkmcnt(0)":::"memory"); \
;       _Pragma("unroll") for(int d_=0;d_<4;++d_) _Pragma("unroll") for(int r=0;r<16;++r)o[d_][r]*=wsf[crow(r,hi)]; } }while(0)
;   #define ROT() do{sl_prev=sl_cur;sl_cur=sl_next;sl_next=(sl_next==(NSLOT-1)*SLOTB)?0:sl_next+SLOTB;}while(0)
; template<int THRL,int MODE> __device__ __forceinline__ void attn_unit(int b,int qb,const bf16*Q,const bf16*__restrict__ K,const bf16*__restrict__ V,bf16*O,bf16*O2,char*shm,bf16*CM,float lam,const float*gn){
;     ...
;   int t=1;
;     ...
;   for(;t+5<NT;t+=2){
;     STEP(pB0,pB1,pA0,pA1,t,true,true,true);     WAIT_BAR(3); RESC(); ROT();
;     STEP(pA0,pA1,pB0,pB1,t+1,true,true,true);   WAIT_BAR(3); RESC(); ROT();
.LBB0_1071:
	s_waitcnt lgkmcnt(14)
	v_mfma_f32_32x32x16_bf16 v[66:81], v[170:173], v[198:201], v[66:81]
	v_exp_f32_e32 v98, v98
	v_exp_f32_e32 v99, v99
	ds_read_b64_tr_b16 v[4:5], v210 offset:32768
	ds_read_b64_tr_b16 v[6:7], v210 offset:33280
	s_waitcnt lgkmcnt(14)
	v_mfma_f32_32x32x16_bf16 v[50:65], v[170:173], v[194:197], v[50:65]
	v_exp_f32_e32 v100, v100
	v_exp_f32_e32 v101, v101
	ds_read_b64_tr_b16 v[12:13], v210 offset:36864
	ds_read_b64_tr_b16 v[14:15], v210 offset:37376
	v_add_u32_e32 v16, s69, v248
	ds_read_b128 v[206:209], v16
	ds_read_b128 v[202:205], v16 offset:512
	s_waitcnt lgkmcnt(14)
	v_mfma_f32_32x32x16_bf16 v[66:81], v[162:165], v[190:193], v[66:81]
	v_exp_f32_e32 v102, v102
	v_exp_f32_e32 v103, v103
	ds_read_b64_tr_b16 v[118:119], v210 offset:33792
	ds_read_b64_tr_b16 v[120:121], v210 offset:34304
	ds_read_b128 v[198:201], v16 offset:2048
	ds_read_b128 v[194:197], v16 offset:2560
	v_mfma_f32_32x32x16_bf16 v[50:65], v[162:165], v[138:141], v[50:65]
	v_exp_f32_e32 v104, v104
	v_exp_f32_e32 v105, v105
	ds_read_b64_tr_b16 v[122:123], v210 offset:37888
	ds_read_b64_tr_b16 v[124:125], v210 offset:38400
	ds_read_b128 v[190:193], v16 offset:4096
	ds_read_b128 v[186:189], v16 offset:4608
	s_waitcnt lgkmcnt(14)
	v_mfma_f32_32x32x16_bf16 v[66:81], v[154:157], v[134:137], v[66:81]
	v_exp_f32_e32 v106, v106
	v_exp_f32_e32 v107, v107
	ds_read_b64_tr_b16 v[126:127], v210 offset:34816
	ds_read_b64_tr_b16 v[128:129], v210 offset:35328
	ds_read_b128 v[182:185], v16 offset:6144
	ds_read_b128 v[178:181], v16 offset:6656
	v_mfma_f32_32x32x16_bf16 v[50:65], v[154:157], v[130:133], v[50:65]
	v_exp_f32_e32 v108, v108
	v_exp_f32_e32 v109, v109
	ds_read_b64_tr_b16 v[130:131], v210 offset:38912
	ds_read_b64_tr_b16 v[132:133], v210 offset:39424
	v_mfma_f32_32x32x16_bf16 v[66:81], v[146:149], v[114:117], v[66:81]
	v_exp_f32_e32 v110, v110
	v_exp_f32_e32 v111, v111
	ds_read_b64_tr_b16 v[114:115], v210 offset:35840
	ds_read_b64_tr_b16 v[116:117], v210 offset:36352
	v_mfma_f32_32x32x16_bf16 v[50:65], v[146:149], v[8:11], v[50:65]
	v_exp_f32_e32 v112, v112
	v_exp_f32_e32 v113, v113
	ds_read_b64_tr_b16 v[8:9], v210 offset:39936
	ds_read_b64_tr_b16 v[10:11], v210 offset:40448
	s_waitcnt lgkmcnt(14)
	v_mfma_f32_32x32x16_bf16 v[34:49], v[170:173], v[4:7], v[34:49]
	v_exp_f32_e32 v82, v82
	v_exp_f32_e32 v83, v83
	v_mfma_f32_32x32x16_bf16 v[18:33], v[170:173], v[12:15], v[18:33]
	v_exp_f32_e32 v84, v84
	v_exp_f32_e32 v85, v85
	v_mfma_f32_32x32x16_bf16 v[34:49], v[162:165], v[118:121], v[34:49]
	v_exp_f32_e32 v86, v86
	v_exp_f32_e32 v87, v87
	s_waitcnt lgkmcnt(12)
	v_mfma_f32_32x32x16_bf16 v[18:33], v[162:165], v[122:125], v[18:33]
	v_exp_f32_e32 v88, v88
	v_exp_f32_e32 v89, v89
	s_waitcnt lgkmcnt(8)
	v_mfma_f32_32x32x16_bf16 v[34:49], v[154:157], v[126:129], v[34:49]
	v_exp_f32_e32 v90, v90
	v_exp_f32_e32 v91, v91
	s_waitcnt lgkmcnt(4)
	v_mfma_f32_32x32x16_bf16 v[18:33], v[154:157], v[130:133], v[18:33]
	v_exp_f32_e32 v92, v92
	v_exp_f32_e32 v93, v93
	s_waitcnt lgkmcnt(2)
	v_mfma_f32_32x32x16_bf16 v[34:49], v[146:149], v[114:117], v[34:49]
	v_exp_f32_e32 v94, v94
	v_exp_f32_e32 v95, v95
	s_waitcnt lgkmcnt(0)
	v_mfma_f32_32x32x16_bf16 v[18:33], v[146:149], v[8:11], v[18:33]
	v_exp_f32_e32 v96, v96
	v_exp_f32_e32 v97, v97
	s_waitcnt vmcnt(3) lgkmcnt(0)
	s_barrier
	s_andn2_b64 vcc, exec, s[40:41]
	s_cbranch_vccnz .LBB0_1073
	s_waitcnt lgkmcnt(0)
	ds_read_b128 v[4:7], v2 offset:96
	ds_read_b128 v[8:11], v2 offset:64
	ds_read_b128 v[12:15], v2 offset:32
	ds_read_b128 v[114:117], v2
	s_waitcnt lgkmcnt(3)
	v_pk_mul_f32 v[78:79], v[78:79], v[4:5]
	s_waitcnt lgkmcnt(2)
	v_pk_mul_f32 v[74:75], v[74:75], v[8:9]
	s_waitcnt lgkmcnt(1)
	v_pk_mul_f32 v[70:71], v[70:71], v[12:13]
	v_pk_mul_f32 v[80:81], v[80:81], v[6:7]
	v_pk_mul_f32 v[76:77], v[76:77], v[10:11]
	v_pk_mul_f32 v[72:73], v[72:73], v[14:15]
	s_waitcnt lgkmcnt(0)
	v_pk_mul_f32 v[68:69], v[68:69], v[116:117]
	v_pk_mul_f32 v[66:67], v[66:67], v[114:115]
	v_pk_mul_f32 v[62:63], v[62:63], v[4:5]
	v_pk_mul_f32 v[58:59], v[58:59], v[8:9]
	v_pk_mul_f32 v[54:55], v[54:55], v[12:13]
	v_pk_mul_f32 v[64:65], v[64:65], v[6:7]
	v_pk_mul_f32 v[60:61], v[60:61], v[10:11]
	v_pk_mul_f32 v[56:57], v[56:57], v[14:15]
	v_pk_mul_f32 v[52:53], v[52:53], v[116:117]
	v_pk_mul_f32 v[50:51], v[50:51], v[114:115]
	v_pk_mul_f32 v[46:47], v[46:47], v[4:5]
	v_pk_mul_f32 v[42:43], v[42:43], v[8:9]
	v_pk_mul_f32 v[38:39], v[38:39], v[12:13]
	v_pk_mul_f32 v[48:49], v[48:49], v[6:7]
	v_pk_mul_f32 v[44:45], v[44:45], v[10:11]
	v_pk_mul_f32 v[40:41], v[40:41], v[14:15]
	v_pk_mul_f32 v[36:37], v[36:37], v[116:117]
	v_pk_mul_f32 v[34:35], v[34:35], v[114:115]
	v_pk_mul_f32 v[30:31], v[30:31], v[4:5]
	v_pk_mul_f32 v[26:27], v[26:27], v[8:9]
	v_pk_mul_f32 v[22:23], v[22:23], v[12:13]
	v_pk_mul_f32 v[32:33], v[32:33], v[6:7]
	v_pk_mul_f32 v[28:29], v[28:29], v[10:11]
	v_pk_mul_f32 v[24:25], v[24:25], v[14:15]
	v_pk_mul_f32 v[20:21], v[20:21], v[116:117]
	v_pk_mul_f32 v[18:19], v[18:19], v[114:115]

.Lnm_exit0:
	v_mov_b32_e32 v224, v216
	v_mov_b32_e32 v225, v217
	v_mov_b32_e32 v226, v252
	v_mov_b32_e32 v227, v253
	v_lshl_add_u64 v[228:229], v[226:227], 0, s[16:17]
	v_mov_b32_e32 v222, s98
	v_mov_b32_e32 v223, s99
	s_branch .LBB0_1082
.LBB0_1075:
	v_max_f32_e32 v82, v82, v82
	v_max_f32_e32 v83, 0, v82
	v_exp_f32_e64 v82, -v83
	s_and_saveexec_b64 s[42:43], s[8:9]
	ds_write_b32 v244, v82
	s_or_b64 exec, exec, s[42:43]
	v_add_f32_e32 v246, v246, v83
	v_sub_f32_e32 v218, v218, v83
	v_sub_f32_e32 v219, v219, v83
	v_sub_f32_e32 v220, v220, v83
	v_sub_f32_e32 v221, v221, v83
	v_sub_f32_e32 v222, v222, v83
	v_sub_f32_e32 v223, v223, v83
	v_sub_f32_e32 v224, v224, v83
	v_sub_f32_e32 v225, v225, v83
	v_sub_f32_e32 v226, v226, v83
	v_sub_f32_e32 v227, v227, v83
	v_sub_f32_e32 v228, v228, v83
	v_sub_f32_e32 v229, v229, v83
	v_sub_f32_e32 v230, v230, v83
	v_sub_f32_e32 v231, v231, v83
	v_sub_f32_e32 v232, v232, v83
	v_sub_f32_e32 v233, v233, v83
	v_sub_f32_e32 v130, v130, v83
	v_sub_f32_e32 v131, v131, v83
	v_sub_f32_e32 v132, v132, v83
	v_sub_f32_e32 v133, v133, v83
	v_sub_f32_e32 v134, v134, v83
	v_sub_f32_e32 v135, v135, v83
	v_sub_f32_e32 v136, v136, v83
	v_sub_f32_e32 v137, v137, v83
	v_sub_f32_e32 v138, v138, v83
	v_sub_f32_e32 v139, v139, v83
	v_sub_f32_e32 v140, v140, v83
	v_sub_f32_e32 v141, v141, v83
	v_sub_f32_e32 v142, v142, v83
	v_sub_f32_e32 v143, v143, v83
	v_sub_f32_e32 v144, v144, v83
	v_sub_f32_e32 v145, v145, v83
	v_sub_f32_e32 v114, v114, v83
	v_sub_f32_e32 v115, v115, v83
	v_sub_f32_e32 v116, v116, v83
	v_sub_f32_e32 v117, v117, v83
	v_sub_f32_e32 v118, v118, v83
	v_sub_f32_e32 v119, v119, v83
	v_sub_f32_e32 v120, v120, v83
	v_sub_f32_e32 v121, v121, v83
	v_sub_f32_e32 v122, v122, v83
	v_sub_f32_e32 v123, v123, v83
	v_sub_f32_e32 v124, v124, v83
	v_sub_f32_e32 v125, v125, v83
	v_sub_f32_e32 v126, v126, v83
	v_sub_f32_e32 v127, v127, v83
	v_sub_f32_e32 v128, v128, v83
	v_sub_f32_e32 v129, v129, v83
	s_nop 1
	v_mul_f32_e32 v215, v215, v82
	s_branch .LBB0_1068
.LBB0_1078:
	v_max_f32_e32 v4, v4, v4
	v_max_f32_e32 v5, 0, v4
	v_exp_f32_e64 v4, -v5
	s_and_saveexec_b64 s[42:43], s[8:9]
	ds_write_b32 v244, v4
	s_or_b64 exec, exec, s[42:43]
	v_add_f32_e32 v246, v246, v5
	v_sub_f32_e32 v218, v218, v5
	v_sub_f32_e32 v219, v219, v5
	v_sub_f32_e32 v220, v220, v5
	v_sub_f32_e32 v221, v221, v5
	v_sub_f32_e32 v222, v222, v5
	v_sub_f32_e32 v223, v223, v5
	v_sub_f32_e32 v224, v224, v5
	v_sub_f32_e32 v225, v225, v5
	v_sub_f32_e32 v226, v226, v5
	v_sub_f32_e32 v227, v227, v5
	v_sub_f32_e32 v228, v228, v5
	v_sub_f32_e32 v229, v229, v5
	v_sub_f32_e32 v230, v230, v5
	v_sub_f32_e32 v231, v231, v5
	v_sub_f32_e32 v232, v232, v5
	v_sub_f32_e32 v233, v233, v5
	v_sub_f32_e32 v98, v98, v5
	v_sub_f32_e32 v99, v99, v5
	v_sub_f32_e32 v100, v100, v5
	v_sub_f32_e32 v101, v101, v5
	v_sub_f32_e32 v102, v102, v5
	v_sub_f32_e32 v103, v103, v5
	v_sub_f32_e32 v104, v104, v5
	v_sub_f32_e32 v105, v105, v5
	v_sub_f32_e32 v106, v106, v5
	v_sub_f32_e32 v107, v107, v5
	v_sub_f32_e32 v108, v108, v5
	v_sub_f32_e32 v109, v109, v5
	v_sub_f32_e32 v110, v110, v5
	v_sub_f32_e32 v111, v111, v5
	v_sub_f32_e32 v112, v112, v5
	v_sub_f32_e32 v113, v113, v5
	v_sub_f32_e32 v82, v82, v5
	v_sub_f32_e32 v83, v83, v5
	v_sub_f32_e32 v84, v84, v5
	v_sub_f32_e32 v85, v85, v5
	v_sub_f32_e32 v86, v86, v5
	v_sub_f32_e32 v87, v87, v5
	v_sub_f32_e32 v88, v88, v5
	v_sub_f32_e32 v89, v89, v5
	v_sub_f32_e32 v90, v90, v5
	v_sub_f32_e32 v91, v91, v5
	v_sub_f32_e32 v92, v92, v5
	v_sub_f32_e32 v93, v93, v5
	v_sub_f32_e32 v94, v94, v5
	v_sub_f32_e32 v95, v95, v5
	v_sub_f32_e32 v96, v96, v5
	v_sub_f32_e32 v97, v97, v5
	s_nop 1
	v_mul_f32_e32 v251, v251, v4
	s_branch .LBB0_1071

; #define WAIT_BAR(N) asm volatile("s_waitcnt vmcnt(" #N ") lgkmcnt(0)\n\ts_barrier":::"memory")
;   #define DMA_K(t,slot) glds16(ksrc+(long)(t)*KVBLK*DM,(unsigned)__builtin_amdgcn_readfirstlane(kdst+(slot)))
;   #define DMA_V(t,slot) do{ glds16(vsrc+(long)(t)*KVBLK*DM,(unsigned)__builtin_amdgcn_readfirstlane(vdst+2*(slot))); glds16(vsrc+64+(long)(t)*KVBLK*DM,(unsigned)__builtin_amdgcn_readfirstlane(vdst+2*(slot)+8192)); }while(0)
;   #define CMASK(P0,P1,t) do{int jb_=(t)-(NT-4); if(jb_>=0)cmask(P0,P1,jb_,qrel,hi);}while(0)
;   #define START(P0,P1) do{ const float rm=rowmax(P0,P1); resc=false; mhat=fadd_s(mhat,rm); \
;     _Pragma("unroll") for(int r=0;r<16;++r){P0[r]=fsub_s(P0[r],mhat);P1[r]=fsub_s(P1[r],mhat);} \
;     _Pragma("unroll") for(int r=0;r<16;++r)P0[r]=__builtin_amdgcn_exp2f(P0[r]); }while(0)
;   #define ROT() do{sl_prev=sl_cur;sl_cur=sl_next;sl_next=(sl_next==(NSLOT-1)*SLOTB)?0:sl_next+SLOTB;}while(0)
;   #define CMASK(P0,P1,t) do{}while(0)
;   #define CMASK(P0,P1,t) do{int jb_=(t)-(NT-4); if(jb_>=0)cmask(P0,P1,jb_,qrel,hi);}while(0)
; template<int THRL,int MODE> __device__ __forceinline__ void attn_unit(int b,int qb,const bf16*Q,const bf16*__restrict__ K,const bf16*__restrict__ V,bf16*O,bf16*O2,char*shm,bf16*CM,float lam,const float*gn){
;     ...
;   f32x16 pA0,pA1,pB0,pB1;
;   int sl_prev=0,sl_cur=0,sl_next=SLOTB;
;     ...
;   DMA_K(2,2*SLOTB);
;   WAIT_BAR(4);
;   qkt(pA0,pA1,Kbase,qr,r32,hi);asm volatile("s_nop 15\n\ts_nop 7":"+v"(pA0),"+v"(pA1));CMASK(pA0,pA1,0);
;   START(pA0,pA1);
;   _Pragma("unroll") for(int r=0;r<16;++r)pA1[r]=__builtin_amdgcn_exp2f(pA1[r]);
;   WAIT_BAR(0);
;   DMA_K(3,0);DMA_V(1,SLOTB);
;   ROT();
;   kload8(kf,kp0+sl_cur);
;   WAIT_BAR(3);
;   s16x4 vlo[8],vhi[8]; u32x4 pw0,pw1,pw2,pw3;
.LBB0_1094:
	v_lshlrev_b32_e32 v2, 1, v36
	v_and_b32_e32 v245, 32, v2
	v_lshlrev_b32_e32 v2, 4, v36
	v_and_b32_e32 v2, 0xc0, v2
	v_lshl_or_b32 v243, v214, 8, v2
	v_add_u32_e32 v2, 0, v245
	v_add3_u32 v249, v2, v242, v243
	v_max3_f32 v2, v20, v21, v4
	v_max3_f32 v36, v22, v23, v5
	s_and_b32 s1, s1, 0x3fffffc0
	v_max3_f32 v2, v2, v6, v7
	v_max3_f32 v36, v36, v26, v27
	s_lshl_b32 s1, s1, 2
	v_max3_f32 v2, v2, v24, v25
	v_max3_f32 v36, v36, v10, v11
	s_add_i32 s45, s1, 0
	v_max3_f32 v2, v2, v8, v9
	v_max3_f32 v36, v36, v30, v31
	s_add_i32 s45, s45, 0x12000
	v_max3_f32 v2, v2, v28, v29
	v_max3_f32 v36, v36, v14, v15
	s_waitcnt vmcnt(0) lgkmcnt(0)
	s_barrier
	s_cmp_lg_u32 0, -1
	v_max3_f32 v2, v2, v12, v13
	v_max3_f32 v36, v36, v34, v35
	s_mov_b32 s14, 1
	v_max3_f32 v2, v2, v32, v33
	v_max3_f32 v36, v36, v18, v19
	s_mov_b32 s1, 0
	v_max3_f32 v2, v2, v16, v17
	v_lshlrev_b32_e32 v250, 4, v214
	v_max_f32_e32 v2, v2, v36
	v_lshl_add_u32 v244, v239, 2, s45
	v_mov_b32_e32 v36, v2
	s_nop 1
	v_permlane32_swap_b32_e32 v2, v36
	v_max_f32_e32 v2, v2, v36
	s_nop 0
	v_add_f32_e32 v246, v3, v2
	s_nop 0
	v_sub_f32_e32 v4, v4, v246
	v_sub_f32_e32 v5, v5, v246
	v_sub_f32_e32 v2, v20, v246
	v_sub_f32_e32 v20, v21, v246
	v_sub_f32_e32 v21, v22, v246
	v_sub_f32_e32 v6, v6, v246
	s_nop 0
	v_exp_f32_e32 v82, v4
	v_exp_f32_e32 v83, v5
	v_lshl_add_u64 v[4:5], v[224:225], 0, s[22:23]
	s_mov_b32 s2, m0
	s_mov_b32 m0, s46
	s_nop 0
	global_load_lds_dwordx4 v[4:5], off
	s_mov_b32 m0, s2
	s_cselect_b32 s2, 0, 0
	s_add_i32 s0, s2, s0
	v_lshl_add_u64 v[4:5], v[226:227], 0, s[18:19]
	s_add_i32 s2, s0, 0xa000
	s_mov_b32 s4, m0
	s_mov_b32 m0, s2
	s_nop 0
	global_load_lds_dwordx4 v[4:5], off
	s_mov_b32 m0, s4
	v_lshl_add_u64 v[4:5], v[226:227], 0, s[24:25]
	s_add_i32 s0, s0, 0xc000
	s_mov_b32 s2, m0
	s_mov_b32 m0, s0
	s_nop 0
	global_load_lds_dwordx4 v[4:5], off
	s_mov_b32 m0, s2
	ds_read_b128 v[206:209], v248 offset:8192
	ds_read_b128 v[202:205], v248 offset:8704
	ds_read_b128 v[198:201], v248 offset:10240
	ds_read_b128 v[194:197], v248 offset:10752
	ds_read_b128 v[190:193], v248 offset:12288
	ds_read_b128 v[186:189], v248 offset:12800
	ds_read_b128 v[182:185], v248 offset:14336
	ds_read_b128 v[178:181], v248 offset:14848
	v_sub_f32_e32 v22, v23, v246
	v_sub_f32_e32 v7, v7, v246
	v_sub_f32_e32 v23, v24, v246
	v_sub_f32_e32 v8, v8, v246
	v_sub_f32_e32 v24, v25, v246
	v_sub_f32_e32 v9, v9, v246
	v_sub_f32_e32 v25, v26, v246
	v_sub_f32_e32 v10, v10, v246
	v_sub_f32_e32 v26, v27, v246
	v_sub_f32_e32 v11, v11, v246
	v_sub_f32_e32 v27, v28, v246
	v_sub_f32_e32 v12, v12, v246
	v_sub_f32_e32 v28, v29, v246
	v_sub_f32_e32 v13, v13, v246
	v_sub_f32_e32 v29, v30, v246
	v_sub_f32_e32 v14, v14, v246
	v_sub_f32_e32 v30, v31, v246
	v_sub_f32_e32 v15, v15, v246
	v_sub_f32_e32 v31, v32, v246
	v_sub_f32_e32 v16, v16, v246
	v_sub_f32_e32 v32, v33, v246
	v_sub_f32_e32 v17, v17, v246
	v_sub_f32_e32 v33, v34, v246
	v_sub_f32_e32 v18, v18, v246
	v_sub_f32_e32 v34, v35, v246
	v_sub_f32_e32 v19, v19, v246
	v_exp_f32_e32 v98, v2
	v_exp_f32_e32 v99, v20
	v_exp_f32_e32 v100, v21
	v_exp_f32_e32 v101, v22
	v_exp_f32_e32 v102, v23
	v_exp_f32_e32 v103, v24
	v_exp_f32_e32 v104, v25
	v_exp_f32_e32 v105, v26
	v_exp_f32_e32 v106, v27
	v_exp_f32_e32 v107, v28
	v_exp_f32_e32 v108, v29
	v_exp_f32_e32 v109, v30
	v_exp_f32_e32 v110, v31
	v_exp_f32_e32 v111, v32
	v_exp_f32_e32 v112, v33
	v_exp_f32_e32 v113, v34
	v_exp_f32_e32 v84, v6
	v_exp_f32_e32 v85, v7
	v_exp_f32_e32 v86, v8
	v_exp_f32_e32 v87, v9
	v_exp_f32_e32 v88, v10
	v_exp_f32_e32 v89, v11
	v_exp_f32_e32 v90, v12
	v_exp_f32_e32 v91, v13
	v_exp_f32_e32 v92, v14
	v_exp_f32_e32 v93, v15
	v_exp_f32_e32 v94, v16
	v_exp_f32_e32 v95, v17
	v_exp_f32_e32 v96, v18
	v_exp_f32_e32 v97, v19
	s_waitcnt vmcnt(3) lgkmcnt(0)
	s_barrier
	s_and_b64 vcc, exec, s[6:7]
	v_cmp_gt_u32_e64 s[6:7], 32, v238
	s_cbranch_vccnz .LBB0_1160
	v_mov_b32_e32 v16, v3
	v_mov_b32_e32 v17, v3
	v_mov_b32_e32 v2, v3
	v_mov_b32_e32 v4, v3
	v_mov_b32_e32 v5, v3
	v_mov_b32_e32 v6, v3
	v_mov_b32_e32 v7, v3
	v_mov_b32_e32 v8, v3
	v_mov_b32_e32 v9, v3
	v_mov_b32_e32 v10, v3
	v_mov_b32_e32 v11, v3
	v_mov_b32_e32 v12, v3
	v_mov_b32_e32 v13, v3
	v_mov_b32_e32 v14, v3
	v_mov_b32_e32 v15, v3
	v_mov_b64_e32 v[80:81], v[16:17]
	v_mov_b64_e32 v[64:65], v[16:17]
	v_mov_b64_e32 v[48:49], v[16:17]
	v_mov_b64_e32 v[32:33], v[16:17]
	s_mov_b32 s8, 0
	s_movk_i32 s1, 0x4000
	s_movk_i32 s14, 0x2000
	v_mov_b32_e32 v251, 0
	s_mov_b32 s2, 6
	s_mov_b64 s[4:5], 0
	v_mov_b64_e32 v[78:79], v[14:15]
	v_mov_b64_e32 v[76:77], v[12:13]
	v_mov_b64_e32 v[74:75], v[10:11]
	v_mov_b64_e32 v[72:73], v[8:9]
	v_mov_b64_e32 v[70:71], v[6:7]
	v_mov_b64_e32 v[68:69], v[4:5]
	v_mov_b64_e32 v[66:67], v[2:3]
	v_mov_b64_e32 v[62:63], v[14:15]
	v_mov_b64_e32 v[60:61], v[12:13]
	v_mov_b64_e32 v[58:59], v[10:11]
	v_mov_b64_e32 v[56:57], v[8:9]
	v_mov_b64_e32 v[54:55], v[6:7]
	v_mov_b64_e32 v[52:53], v[4:5]
	v_mov_b64_e32 v[50:51], v[2:3]
	v_mov_b64_e32 v[46:47], v[14:15]
	v_mov_b64_e32 v[44:45], v[12:13]
	v_mov_b64_e32 v[42:43], v[10:11]
	v_mov_b64_e32 v[40:41], v[8:9]
	v_mov_b64_e32 v[38:39], v[6:7]
	v_mov_b64_e32 v[36:37], v[4:5]
	v_mov_b64_e32 v[34:35], v[2:3]
	v_mov_b64_e32 v[30:31], v[14:15]
	v_mov_b64_e32 v[28:29], v[12:13]
	v_mov_b64_e32 v[26:27], v[10:11]
	v_mov_b64_e32 v[24:25], v[8:9]
	v_mov_b64_e32 v[22:23], v[6:7]
	v_mov_b64_e32 v[20:21], v[4:5]
	v_mov_b64_e32 v[18:19], v[2:3]
	v_readfirstlane_b32 s98, v222
	v_readfirstlane_b32 s99, v223
	v_mov_b32_e32 v216, v224
	v_mov_b32_e32 v217, v225
	v_mov_b32_e32 v252, v226
	v_mov_b32_e32 v253, v227
	v_sub_f32_e32 v218, 0, v246
	v_sub_f32_e32 v219, 0, v246
	v_sub_f32_e32 v220, 0, v246
	v_sub_f32_e32 v221, 0, v246
	v_sub_f32_e32 v222, 0, v246
	v_sub_f32_e32 v223, 0, v246
	v_sub_f32_e32 v224, 0, v246
	v_sub_f32_e32 v225, 0, v246
	v_sub_f32_e32 v226, 0, v246
	v_sub_f32_e32 v227, 0, v246
	v_sub_f32_e32 v228, 0, v246
	v_sub_f32_e32 v229, 0, v246
	v_sub_f32_e32 v230, 0, v246
	v_sub_f32_e32 v231, 0, v246
	v_sub_f32_e32 v232, 0, v246
	v_sub_f32_e32 v233, 0, v246
	s_nop 1
.LBB0_1096:
	s_lshl_b32 s0, s8, 1
	v_add_u32_e32 v2, s0, v249
	ds_read_b64_tr_b16 v[210:211], v2 offset:24576
	ds_read_b64_tr_b16 v[212:213], v2 offset:25088
	s_waitcnt lgkmcnt(9)
	v_mfma_f32_32x32x16_bf16 v[130:145], v[206:209], v[174:177], v[218:233]
	v_add_f32_e32 v4, v98, v99
	v_add_f32_e32 v4, v100, v4
	v_add_f32_e32 v4, v101, v4
	v_add_f32_e32 v4, v102, v4
	v_add_f32_e32 v4, v103, v4
	v_cvt_pk_bf16_f32 v166, v98, v99
	v_cvt_pk_bf16_f32 v167, v100, v101
	ds_read_b64_tr_b16 v[206:207], v2 offset:28672
	ds_read_b64_tr_b16 v[208:209], v2 offset:29184
	s_waitcnt lgkmcnt(10)
	v_mfma_f32_32x32x16_bf16 v[114:129], v[202:205], v[174:177], v[218:233]
	v_add_f32_e32 v4, v104, v4
	v_add_f32_e32 v4, v105, v4
	v_add_f32_e32 v4, v106, v4
	v_add_f32_e32 v4, v107, v4
	v_cvt_pk_bf16_f32 v168, v102, v103
	v_cvt_pk_bf16_f32 v169, v104, v105
	ds_read_b64_tr_b16 v[12:13], v2 offset:25600
	ds_read_b64_tr_b16 v[14:15], v2 offset:26112
	s_waitcnt lgkmcnt(11)
	v_mfma_f32_32x32x16_bf16 v[130:145], v[198:201], v[170:173], v[130:145]
	v_add_f32_e32 v4, v108, v4
	v_add_f32_e32 v4, v109, v4
	v_add_f32_e32 v4, v110, v4
	v_add_f32_e32 v4, v111, v4
	v_cvt_pk_bf16_f32 v162, v106, v107
	v_cvt_pk_bf16_f32 v163, v108, v109
	ds_read_b64_tr_b16 v[8:9], v2 offset:29696
	ds_read_b64_tr_b16 v[10:11], v2 offset:30208
	s_waitcnt lgkmcnt(12)
	v_mfma_f32_32x32x16_bf16 v[114:129], v[194:197], v[170:173], v[114:129]
	v_add_f32_e32 v4, v112, v4
	v_add_f32_e32 v4, v113, v4
	v_add_f32_e32 v4, v82, v4
	v_add_f32_e32 v16, v83, v4
	v_cvt_pk_bf16_f32 v164, v110, v111
	v_cvt_pk_bf16_f32 v165, v112, v113
	ds_read_b64_tr_b16 v[4:5], v2 offset:26624
	ds_read_b64_tr_b16 v[6:7], v2 offset:27136
	s_waitcnt lgkmcnt(13)
	v_mfma_f32_32x32x16_bf16 v[130:145], v[190:193], v[158:161], v[130:145]
	v_add_f32_e32 v16, v84, v16
	v_add_f32_e32 v16, v85, v16
	v_add_f32_e32 v16, v86, v16
	v_add_f32_e32 v16, v87, v16
	v_cvt_pk_bf16_f32 v154, v82, v83
	v_cvt_pk_bf16_f32 v155, v84, v85
	ds_read_b64_tr_b16 v[102:103], v2 offset:30720
	ds_read_b64_tr_b16 v[104:105], v2 offset:31232
	s_waitcnt lgkmcnt(14)
	v_mfma_f32_32x32x16_bf16 v[114:129], v[186:189], v[158:161], v[114:129]
	v_add_f32_e32 v16, v88, v16
	v_add_f32_e32 v16, v89, v16
	v_add_f32_e32 v16, v90, v16
	v_add_f32_e32 v16, v91, v16
	v_cvt_pk_bf16_f32 v156, v86, v87
	v_cvt_pk_bf16_f32 v157, v88, v89
	ds_read_b64_tr_b16 v[98:99], v2 offset:27648
	ds_read_b64_tr_b16 v[100:101], v2 offset:28160
	s_waitcnt lgkmcnt(14)
	v_mfma_f32_32x32x16_bf16 v[130:145], v[182:185], v[150:153], v[130:145]
	v_add_f32_e32 v16, v92, v16
	v_add_f32_e32 v16, v93, v16
	v_add_f32_e32 v16, v94, v16
	v_add_f32_e32 v16, v95, v16
	v_cvt_pk_bf16_f32 v146, v90, v91
	v_cvt_pk_bf16_f32 v147, v92, v93
	ds_read_b64_tr_b16 v[90:91], v2 offset:31744
	ds_read_b64_tr_b16 v[92:93], v2 offset:32256
	v_mfma_f32_32x32x16_bf16 v[114:129], v[178:181], v[150:153], v[114:129]
	v_add_f32_e32 v16, v96, v16
	v_add_f32_e32 v16, v97, v16
	v_add_f32_e32 v84, 0, v16
	v_cvt_pk_bf16_f32 v148, v94, v95
	v_cvt_pk_bf16_f32 v149, v96, v97
	v_lshl_add_u64 v[16:17], v[216:217], 0, s[4:5]
	v_lshl_add_u64 v[82:83], v[16:17], 0, s[26:27]
	s_add_i32 s0, s14, s46
	v_lshl_add_u64 v[202:203], v[252:253], 0, s[4:5]
	s_mov_b32 s8, m0
	s_mov_b32 m0, s0
	s_nop 0
	global_load_lds_dwordx4 v[82:83], off
	s_mov_b32 m0, s8
	v_lshl_add_u64 v[82:83], v[202:203], 0, s[20:21]
	s_lshl_b32 s0, s1, 1
	v_lshl_add_u64 v[204:205], v[202:203], 0, s[16:17]
	s_add_i32 s0, s0, s47
	s_mov_b32 s8, m0
	s_mov_b32 m0, s0
	s_nop 0
	global_load_lds_dwordx4 v[82:83], off
	s_mov_b32 m0, s8
	v_lshl_add_u64 v[82:83], v[204:205], 0, s[20:21]
	s_addk_i32 s0, 0x2000
	s_mov_b32 s8, m0
	s_mov_b32 m0, s0
	s_nop 0
	global_load_lds_dwordx4 v[82:83], off
	s_mov_b32 m0, s8
	v_max_f32_e32 v82, v131, v131
	v_max_f32_e32 v83, v130, v130
	v_max_f32_e32 v82, v83, v82
	v_max3_f32 v83, v132, v133, v115
	v_max3_f32 v82, v82, v114, v116
	v_max3_f32 v82, v82, v117, v134
	v_max3_f32 v83, v83, v136, v137
	v_max3_f32 v82, v82, v135, v118
	v_max3_f32 v83, v83, v120, v121
	v_max3_f32 v82, v82, v119, v138
	v_max3_f32 v83, v83, v140, v141
	v_max3_f32 v82, v82, v139, v122
	v_max3_f32 v83, v83, v124, v125
	v_max3_f32 v82, v82, v123, v142
	v_max3_f32 v83, v83, v144, v145
	v_max3_f32 v82, v82, v143, v126
	v_max3_f32 v83, v83, v128, v129
	v_max3_f32 v82, v82, v127, v83
	v_mov_b32_e32 v83, v82
	s_nop 1
	v_permlane32_swap_b32_e32 v82, v83
	v_max_f32_e32 v83, v83, v83
	v_max_f32_e32 v82, v82, v82
	v_max_f32_e32 v82, v82, v83
	v_cmp_lt_f32_e32 vcc, s55, v82
	s_cmp_lg_u64 vcc, 0
	v_add_f32_e32 v215, v251, v84
	s_cselect_b64 s[8:9], -1, 0
	s_cbranch_vccnz .LBB0_1104
.LBB0_1097:
	s_waitcnt lgkmcnt(14)
	v_mfma_f32_32x32x16_bf16 v[66:81], v[166:169], v[210:213], v[66:81]
	v_exp_f32_e32 v130, v130
	v_exp_f32_e32 v131, v131
	ds_read_b64_tr_b16 v[94:95], v2 offset:32768
	ds_read_b64_tr_b16 v[96:97], v2 offset:33280
	s_waitcnt lgkmcnt(14)
	v_mfma_f32_32x32x16_bf16 v[50:65], v[166:169], v[206:209], v[50:65]
	v_exp_f32_e32 v132, v132
	v_exp_f32_e32 v133, v133
	ds_read_b64_tr_b16 v[106:107], v2 offset:36864
	ds_read_b64_tr_b16 v[108:109], v2 offset:37376
	v_add_u32_e32 v198, s1, v248
	ds_read_b128 v[86:89], v198
	ds_read_b128 v[82:85], v198 offset:512
	s_waitcnt lgkmcnt(14)
	v_mfma_f32_32x32x16_bf16 v[66:81], v[162:165], v[12:15], v[66:81]
	v_exp_f32_e32 v134, v134
	v_exp_f32_e32 v135, v135
	ds_read_b64_tr_b16 v[110:111], v2 offset:33792
	ds_read_b64_tr_b16 v[112:113], v2 offset:34304
	ds_read_b128 v[186:189], v198 offset:2048
	ds_read_b128 v[178:181], v198 offset:2560
	v_mfma_f32_32x32x16_bf16 v[50:65], v[162:165], v[8:11], v[50:65]
	v_exp_f32_e32 v136, v136
	v_exp_f32_e32 v137, v137
	ds_read_b64_tr_b16 v[190:191], v2 offset:37888
	ds_read_b64_tr_b16 v[192:193], v2 offset:38400
	ds_read_b128 v[182:185], v198 offset:4096
	ds_read_b128 v[8:11], v198 offset:4608
	s_waitcnt lgkmcnt(14)
	v_mfma_f32_32x32x16_bf16 v[66:81], v[154:157], v[4:7], v[66:81]
	v_exp_f32_e32 v138, v138
	v_exp_f32_e32 v139, v139
	ds_read_b64_tr_b16 v[194:195], v2 offset:34816
	ds_read_b64_tr_b16 v[196:197], v2 offset:35328
	ds_read_b128 v[12:15], v198 offset:6144
	ds_read_b128 v[4:7], v198 offset:6656
	v_mfma_f32_32x32x16_bf16 v[50:65], v[154:157], v[102:105], v[50:65]
	v_exp_f32_e32 v140, v140
	v_exp_f32_e32 v141, v141
	ds_read_b64_tr_b16 v[102:103], v2 offset:38912
	ds_read_b64_tr_b16 v[104:105], v2 offset:39424
	v_mfma_f32_32x32x16_bf16 v[66:81], v[146:149], v[98:101], v[66:81]
	v_exp_f32_e32 v142, v142
	v_exp_f32_e32 v143, v143
	ds_read_b64_tr_b16 v[98:99], v2 offset:35840
	ds_read_b64_tr_b16 v[100:101], v2 offset:36352
	v_mfma_f32_32x32x16_bf16 v[50:65], v[146:149], v[90:93], v[50:65]
	v_exp_f32_e32 v144, v144
	v_exp_f32_e32 v145, v145
	ds_read_b64_tr_b16 v[90:91], v2 offset:39936
	ds_read_b64_tr_b16 v[92:93], v2 offset:40448
	s_waitcnt lgkmcnt(14)
	v_mfma_f32_32x32x16_bf16 v[34:49], v[166:169], v[94:97], v[34:49]
	v_exp_f32_e32 v114, v114
	v_exp_f32_e32 v115, v115
	v_mfma_f32_32x32x16_bf16 v[18:33], v[166:169], v[106:109], v[18:33]
	v_exp_f32_e32 v116, v116
	v_exp_f32_e32 v117, v117
	v_mfma_f32_32x32x16_bf16 v[34:49], v[162:165], v[110:113], v[34:49]
	v_exp_f32_e32 v118, v118
	v_exp_f32_e32 v119, v119
	s_waitcnt lgkmcnt(12)
	v_mfma_f32_32x32x16_bf16 v[18:33], v[162:165], v[190:193], v[18:33]
	v_exp_f32_e32 v120, v120
	v_exp_f32_e32 v121, v121
	s_waitcnt lgkmcnt(8)
	v_mfma_f32_32x32x16_bf16 v[34:49], v[154:157], v[194:197], v[34:49]
	v_exp_f32_e32 v122, v122
	v_exp_f32_e32 v123, v123
	s_waitcnt lgkmcnt(4)
	v_mfma_f32_32x32x16_bf16 v[18:33], v[154:157], v[102:105], v[18:33]
	v_exp_f32_e32 v124, v124
	v_exp_f32_e32 v125, v125
	s_waitcnt lgkmcnt(2)
	v_mfma_f32_32x32x16_bf16 v[34:49], v[146:149], v[98:101], v[34:49]
	v_exp_f32_e32 v126, v126
	v_exp_f32_e32 v127, v127
	s_waitcnt lgkmcnt(0)
	v_mfma_f32_32x32x16_bf16 v[18:33], v[146:149], v[90:93], v[18:33]
	v_exp_f32_e32 v128, v128
	v_exp_f32_e32 v129, v129
	s_waitcnt vmcnt(3) lgkmcnt(0)
	s_barrier
	s_andn2_b64 vcc, exec, s[8:9]
	v_add_u32_e32 v2, s45, v250
	s_cbranch_vccnz .LBB0_1099
	s_waitcnt lgkmcnt(0)
	ds_read_b128 v[90:93], v2 offset:96
	ds_read_b128 v[94:97], v2 offset:64
	ds_read_b128 v[98:101], v2 offset:32
	ds_read_b128 v[102:105], v2
	s_waitcnt lgkmcnt(3)
	v_pk_mul_f32 v[78:79], v[78:79], v[90:91]
	s_waitcnt lgkmcnt(2)
	v_pk_mul_f32 v[74:75], v[74:75], v[94:95]
	s_waitcnt lgkmcnt(1)
	v_pk_mul_f32 v[70:71], v[70:71], v[98:99]
	v_pk_mul_f32 v[80:81], v[80:81], v[92:93]
	v_pk_mul_f32 v[76:77], v[76:77], v[96:97]
	v_pk_mul_f32 v[72:73], v[72:73], v[100:101]
	s_waitcnt lgkmcnt(0)
	v_pk_mul_f32 v[68:69], v[68:69], v[104:105]
	v_pk_mul_f32 v[66:67], v[66:67], v[102:103]
	v_pk_mul_f32 v[62:63], v[62:63], v[90:91]
	v_pk_mul_f32 v[58:59], v[58:59], v[94:95]
	v_pk_mul_f32 v[54:55], v[54:55], v[98:99]
	v_pk_mul_f32 v[64:65], v[64:65], v[92:93]
	v_pk_mul_f32 v[60:61], v[60:61], v[96:97]
	v_pk_mul_f32 v[56:57], v[56:57], v[100:101]
	v_pk_mul_f32 v[52:53], v[52:53], v[104:105]
	v_pk_mul_f32 v[50:51], v[50:51], v[102:103]
	v_pk_mul_f32 v[46:47], v[46:47], v[90:91]
	v_pk_mul_f32 v[42:43], v[42:43], v[94:95]
	v_pk_mul_f32 v[38:39], v[38:39], v[98:99]
	v_pk_mul_f32 v[48:49], v[48:49], v[92:93]
	v_pk_mul_f32 v[44:45], v[44:45], v[96:97]
	v_pk_mul_f32 v[40:41], v[40:41], v[100:101]
	v_pk_mul_f32 v[36:37], v[36:37], v[104:105]
	v_pk_mul_f32 v[34:35], v[34:35], v[102:103]
	v_pk_mul_f32 v[30:31], v[30:31], v[90:91]
	v_pk_mul_f32 v[26:27], v[26:27], v[94:95]
	v_pk_mul_f32 v[22:23], v[22:23], v[98:99]
	v_pk_mul_f32 v[32:33], v[32:33], v[92:93]
	v_pk_mul_f32 v[28:29], v[28:29], v[96:97]
	v_pk_mul_f32 v[24:25], v[24:25], v[100:101]
	v_pk_mul_f32 v[20:21], v[20:21], v[104:105]
	v_pk_mul_f32 v[18:19], v[18:19], v[102:103]
.LBB0_1099:
	s_add_i32 s0, s1, 0x2000
	s_cmpk_lg_i32 s1, 0x4000
	s_cselect_b32 s48, s0, 0
	s_lshl_b32 s0, s14, 1
	v_add_u32_e32 v210, s0, v249
	ds_read_b64_tr_b16 v[198:199], v210 offset:24576
	ds_read_b64_tr_b16 v[200:201], v210 offset:25088
	v_mfma_f32_32x32x16_bf16 v[98:113], v[86:89], v[174:177], v[218:233]
	v_add_f32_e32 v90, v130, v131
	v_add_f32_e32 v90, v132, v90
	v_add_f32_e32 v90, v133, v90
	v_add_f32_e32 v90, v134, v90
	v_add_f32_e32 v90, v135, v90
	v_cvt_pk_bf16_f32 v166, v130, v131
	v_cvt_pk_bf16_f32 v167, v132, v133
	ds_read_b64_tr_b16 v[194:195], v210 offset:28672
	ds_read_b64_tr_b16 v[196:197], v210 offset:29184
	v_add_f32_e32 v86, v136, v90
	v_add_f32_e32 v86, v137, v86
	v_add_f32_e32 v86, v138, v86
	v_add_f32_e32 v130, v139, v86
	v_mfma_f32_32x32x16_bf16 v[82:97], v[82:85], v[174:177], v[218:233]
	v_cvt_pk_bf16_f32 v168, v134, v135
	v_cvt_pk_bf16_f32 v169, v136, v137
	ds_read_b64_tr_b16 v[190:191], v210 offset:25600
	ds_read_b64_tr_b16 v[192:193], v210 offset:26112
	v_mfma_f32_32x32x16_bf16 v[98:113], v[186:189], v[170:173], v[98:113]
	v_add_f32_e32 v130, v140, v130
	v_add_f32_e32 v130, v141, v130
	v_add_f32_e32 v130, v142, v130
	v_add_f32_e32 v130, v143, v130
	v_cvt_pk_bf16_f32 v162, v138, v139
	v_cvt_pk_bf16_f32 v163, v140, v141
	ds_read_b64_tr_b16 v[138:139], v210 offset:29696
	ds_read_b64_tr_b16 v[140:141], v210 offset:30208
	v_mfma_f32_32x32x16_bf16 v[82:97], v[178:181], v[170:173], v[82:97]
	v_add_f32_e32 v130, v144, v130
	v_add_f32_e32 v130, v145, v130
	v_add_f32_e32 v130, v114, v130
	v_add_f32_e32 v130, v115, v130
	v_cvt_pk_bf16_f32 v164, v142, v143
	v_cvt_pk_bf16_f32 v165, v144, v145
	ds_read_b64_tr_b16 v[134:135], v210 offset:26624
	ds_read_b64_tr_b16 v[136:137], v210 offset:27136
	v_mfma_f32_32x32x16_bf16 v[98:113], v[182:185], v[158:161], v[98:113]
	v_add_f32_e32 v130, v116, v130
	v_add_f32_e32 v130, v117, v130
	v_add_f32_e32 v130, v118, v130
	v_add_f32_e32 v142, v119, v130
	v_cvt_pk_bf16_f32 v154, v114, v115
	v_cvt_pk_bf16_f32 v155, v116, v117
	ds_read_b64_tr_b16 v[130:131], v210 offset:30720
	ds_read_b64_tr_b16 v[132:133], v210 offset:31232
	v_mfma_f32_32x32x16_bf16 v[82:97], v[8:11], v[158:161], v[82:97]
	v_add_f32_e32 v114, v120, v142
	v_add_f32_e32 v114, v121, v114
	v_add_f32_e32 v114, v122, v114
	v_add_f32_e32 v142, v123, v114
	v_cvt_pk_bf16_f32 v156, v118, v119
	v_cvt_pk_bf16_f32 v157, v120, v121
	ds_read_b64_tr_b16 v[114:115], v210 offset:27648
	ds_read_b64_tr_b16 v[116:117], v210 offset:28160
	v_mfma_f32_32x32x16_bf16 v[98:113], v[12:15], v[150:153], v[98:113]
	v_add_f32_e32 v8, v124, v142
	v_add_f32_e32 v8, v125, v8
	v_add_f32_e32 v8, v126, v8
	v_add_f32_e32 v118, v127, v8
	v_cvt_pk_bf16_f32 v146, v122, v123
	v_cvt_pk_bf16_f32 v147, v124, v125
	ds_read_b64_tr_b16 v[8:9], v210 offset:31744
	ds_read_b64_tr_b16 v[10:11], v210 offset:32256
	v_mfma_f32_32x32x16_bf16 v[82:97], v[4:7], v[150:153], v[82:97]
	v_add_f32_e32 v12, v128, v118
	v_add_f32_e32 v12, v129, v12
	v_add_f32_e32 v12, 0, v12
	v_cvt_pk_bf16_f32 v148, v126, v127
	v_cvt_pk_bf16_f32 v149, v128, v129
	v_lshl_add_u64 v[4:5], v[16:17], 0, s[28:29]
	s_add_i32 s0, s1, s46
	s_mov_b32 s8, m0
	s_mov_b32 m0, s0
	s_nop 0
	global_load_lds_dwordx4 v[4:5], off
	s_mov_b32 m0, s8
	v_lshl_add_u64 v[4:5], v[202:203], 0, s[22:23]
	s_lshl_b32 s0, s48, 1
	s_add_i32 s0, s0, s47
	s_mov_b32 s8, m0
	s_mov_b32 m0, s0
	s_nop 0
	global_load_lds_dwordx4 v[4:5], off
	s_mov_b32 m0, s8
	v_lshl_add_u64 v[4:5], v[204:205], 0, s[22:23]
	s_addk_i32 s0, 0x2000
	s_mov_b32 s8, m0
	s_mov_b32 m0, s0
	s_nop 0
	global_load_lds_dwordx4 v[4:5], off
	s_mov_b32 m0, s8
	v_max_f32_e32 v4, v99, v99
	v_max_f32_e32 v5, v98, v98
	v_max_f32_e32 v4, v5, v4
	v_max3_f32 v5, v100, v101, v83
	v_max3_f32 v4, v4, v82, v84
	v_max3_f32 v4, v4, v85, v102
	v_max3_f32 v5, v5, v104, v105
	v_max3_f32 v4, v4, v103, v86
	v_max3_f32 v5, v5, v88, v89
	v_max3_f32 v4, v4, v87, v106
	v_max3_f32 v5, v5, v108, v109
	v_max3_f32 v4, v4, v107, v90
	v_max3_f32 v5, v5, v92, v93
	v_max3_f32 v4, v4, v91, v110
	v_max3_f32 v5, v5, v112, v113
	v_max3_f32 v4, v4, v111, v94
	v_max3_f32 v5, v5, v96, v97
	v_max3_f32 v4, v4, v95, v5
	v_mov_b32_e32 v5, v4
	s_nop 1
	v_permlane32_swap_b32_e32 v4, v5
	v_max_f32_e32 v5, v5, v5
	v_max_f32_e32 v4, v4, v4
	v_max_f32_e32 v4, v4, v5
	v_cmp_lt_f32_e32 vcc, s55, v4
	s_cmp_lg_u64 vcc, 0
	v_add_f32_e32 v251, v215, v12
	s_cselect_b64 s[8:9], -1, 0
	s_cbranch_vccnz .LBB0_1107
.LBB0_1100:
	s_waitcnt lgkmcnt(14)
	v_mfma_f32_32x32x16_bf16 v[66:81], v[166:169], v[198:201], v[66:81]
	v_exp_f32_e32 v98, v98
	v_exp_f32_e32 v99, v99
	ds_read_b64_tr_b16 v[4:5], v210 offset:32768
	ds_read_b64_tr_b16 v[6:7], v210 offset:33280
	s_waitcnt lgkmcnt(14)
	v_mfma_f32_32x32x16_bf16 v[50:65], v[166:169], v[194:197], v[50:65]
	v_exp_f32_e32 v100, v100
	v_exp_f32_e32 v101, v101
	ds_read_b64_tr_b16 v[12:13], v210 offset:36864
	ds_read_b64_tr_b16 v[14:15], v210 offset:37376
	v_add_u32_e32 v16, s48, v248
	ds_read_b128 v[206:209], v16
	ds_read_b128 v[202:205], v16 offset:512
	s_waitcnt lgkmcnt(14)
	v_mfma_f32_32x32x16_bf16 v[66:81], v[162:165], v[190:193], v[66:81]
	v_exp_f32_e32 v102, v102
	v_exp_f32_e32 v103, v103
	ds_read_b64_tr_b16 v[118:119], v210 offset:33792
	ds_read_b64_tr_b16 v[120:121], v210 offset:34304
	ds_read_b128 v[198:201], v16 offset:2048
	ds_read_b128 v[194:197], v16 offset:2560
	v_mfma_f32_32x32x16_bf16 v[50:65], v[162:165], v[138:141], v[50:65]
	v_exp_f32_e32 v104, v104
	v_exp_f32_e32 v105, v105
	ds_read_b64_tr_b16 v[122:123], v210 offset:37888
	ds_read_b64_tr_b16 v[124:125], v210 offset:38400
	ds_read_b128 v[190:193], v16 offset:4096
	ds_read_b128 v[186:189], v16 offset:4608
	s_waitcnt lgkmcnt(14)
	v_mfma_f32_32x32x16_bf16 v[66:81], v[154:157], v[134:137], v[66:81]
	v_exp_f32_e32 v106, v106
	v_exp_f32_e32 v107, v107
	ds_read_b64_tr_b16 v[126:127], v210 offset:34816
	ds_read_b64_tr_b16 v[128:129], v210 offset:35328
	ds_read_b128 v[182:185], v16 offset:6144
	ds_read_b128 v[178:181], v16 offset:6656
	v_mfma_f32_32x32x16_bf16 v[50:65], v[154:157], v[130:133], v[50:65]
	v_exp_f32_e32 v108, v108
	v_exp_f32_e32 v109, v109
	ds_read_b64_tr_b16 v[130:131], v210 offset:38912
	ds_read_b64_tr_b16 v[132:133], v210 offset:39424
	v_mfma_f32_32x32x16_bf16 v[66:81], v[146:149], v[114:117], v[66:81]
	v_exp_f32_e32 v110, v110
	v_exp_f32_e32 v111, v111
	ds_read_b64_tr_b16 v[114:115], v210 offset:35840
	ds_read_b64_tr_b16 v[116:117], v210 offset:36352
	v_mfma_f32_32x32x16_bf16 v[50:65], v[146:149], v[8:11], v[50:65]
	v_exp_f32_e32 v112, v112
	v_exp_f32_e32 v113, v113
	ds_read_b64_tr_b16 v[8:9], v210 offset:39936
	ds_read_b64_tr_b16 v[10:11], v210 offset:40448
	s_waitcnt lgkmcnt(14)
	v_mfma_f32_32x32x16_bf16 v[34:49], v[166:169], v[4:7], v[34:49]
	v_exp_f32_e32 v82, v82
	v_exp_f32_e32 v83, v83
	v_mfma_f32_32x32x16_bf16 v[18:33], v[166:169], v[12:15], v[18:33]
	v_exp_f32_e32 v84, v84
	v_exp_f32_e32 v85, v85
	v_mfma_f32_32x32x16_bf16 v[34:49], v[162:165], v[118:121], v[34:49]
	v_exp_f32_e32 v86, v86
	v_exp_f32_e32 v87, v87
	s_waitcnt lgkmcnt(12)
	v_mfma_f32_32x32x16_bf16 v[18:33], v[162:165], v[122:125], v[18:33]
	v_exp_f32_e32 v88, v88
	v_exp_f32_e32 v89, v89
	s_waitcnt lgkmcnt(8)
	v_mfma_f32_32x32x16_bf16 v[34:49], v[154:157], v[126:129], v[34:49]
	v_exp_f32_e32 v90, v90
	v_exp_f32_e32 v91, v91
	s_waitcnt lgkmcnt(4)
	v_mfma_f32_32x32x16_bf16 v[18:33], v[154:157], v[130:133], v[18:33]
	v_exp_f32_e32 v92, v92
	v_exp_f32_e32 v93, v93
	s_waitcnt lgkmcnt(2)
	v_mfma_f32_32x32x16_bf16 v[34:49], v[146:149], v[114:117], v[34:49]
	v_exp_f32_e32 v94, v94
	v_exp_f32_e32 v95, v95
	s_waitcnt lgkmcnt(0)
	v_mfma_f32_32x32x16_bf16 v[18:33], v[146:149], v[8:11], v[18:33]
	v_exp_f32_e32 v96, v96
	v_exp_f32_e32 v97, v97
	s_waitcnt vmcnt(3) lgkmcnt(0)
	s_barrier
	s_andn2_b64 vcc, exec, s[8:9]
	s_cbranch_vccnz .LBB0_1102
	s_waitcnt lgkmcnt(0)
	ds_read_b128 v[4:7], v2 offset:96
	ds_read_b128 v[8:11], v2 offset:64
	ds_read_b128 v[12:15], v2 offset:32
	ds_read_b128 v[114:117], v2
	s_waitcnt lgkmcnt(3)
	v_pk_mul_f32 v[78:79], v[78:79], v[4:5]
	s_waitcnt lgkmcnt(2)
	v_pk_mul_f32 v[74:75], v[74:75], v[8:9]
	s_waitcnt lgkmcnt(1)
	v_pk_mul_f32 v[70:71], v[70:71], v[12:13]
	v_pk_mul_f32 v[80:81], v[80:81], v[6:7]
	v_pk_mul_f32 v[76:77], v[76:77], v[10:11]
	v_pk_mul_f32 v[72:73], v[72:73], v[14:15]
	s_waitcnt lgkmcnt(0)
	v_pk_mul_f32 v[68:69], v[68:69], v[116:117]
	v_pk_mul_f32 v[66:67], v[66:67], v[114:115]
	v_pk_mul_f32 v[62:63], v[62:63], v[4:5]
	v_pk_mul_f32 v[58:59], v[58:59], v[8:9]
	v_pk_mul_f32 v[54:55], v[54:55], v[12:13]
	v_pk_mul_f32 v[64:65], v[64:65], v[6:7]
	v_pk_mul_f32 v[60:61], v[60:61], v[10:11]
	v_pk_mul_f32 v[56:57], v[56:57], v[14:15]
	v_pk_mul_f32 v[52:53], v[52:53], v[116:117]
	v_pk_mul_f32 v[50:51], v[50:51], v[114:115]
	v_pk_mul_f32 v[46:47], v[46:47], v[4:5]
	v_pk_mul_f32 v[42:43], v[42:43], v[8:9]
	v_pk_mul_f32 v[38:39], v[38:39], v[12:13]
	v_pk_mul_f32 v[48:49], v[48:49], v[6:7]
	v_pk_mul_f32 v[44:45], v[44:45], v[10:11]
	v_pk_mul_f32 v[40:41], v[40:41], v[14:15]
	v_pk_mul_f32 v[36:37], v[36:37], v[116:117]
	v_pk_mul_f32 v[34:35], v[34:35], v[114:115]
	v_pk_mul_f32 v[30:31], v[30:31], v[4:5]
	v_pk_mul_f32 v[26:27], v[26:27], v[8:9]
	v_pk_mul_f32 v[22:23], v[22:23], v[12:13]
	v_pk_mul_f32 v[32:33], v[32:33], v[6:7]
	v_pk_mul_f32 v[28:29], v[28:29], v[10:11]
	v_pk_mul_f32 v[24:25], v[24:25], v[14:15]
	v_pk_mul_f32 v[20:21], v[20:21], v[116:117]
	v_pk_mul_f32 v[18:19], v[18:19], v[114:115]

.LBB0_1104:
	v_max_f32_e32 v82, v82, v82
	v_max_f32_e32 v83, 0, v82
	v_exp_f32_e64 v82, -v83
	s_and_saveexec_b64 s[30:31], s[6:7]
	ds_write_b32 v244, v82
	s_or_b64 exec, exec, s[30:31]
	v_add_f32_e32 v246, v246, v83
	v_sub_f32_e32 v218, v218, v83
	v_sub_f32_e32 v219, v219, v83
	v_sub_f32_e32 v220, v220, v83
	v_sub_f32_e32 v221, v221, v83
	v_sub_f32_e32 v222, v222, v83
	v_sub_f32_e32 v223, v223, v83
	v_sub_f32_e32 v224, v224, v83
	v_sub_f32_e32 v225, v225, v83
	v_sub_f32_e32 v226, v226, v83
	v_sub_f32_e32 v227, v227, v83
	v_sub_f32_e32 v228, v228, v83
	v_sub_f32_e32 v229, v229, v83
	v_sub_f32_e32 v230, v230, v83
	v_sub_f32_e32 v231, v231, v83
	v_sub_f32_e32 v232, v232, v83
	v_sub_f32_e32 v233, v233, v83
	v_sub_f32_e32 v130, v130, v83
	v_sub_f32_e32 v131, v131, v83
	v_sub_f32_e32 v132, v132, v83
	v_sub_f32_e32 v133, v133, v83
	v_sub_f32_e32 v134, v134, v83
	v_sub_f32_e32 v135, v135, v83
	v_sub_f32_e32 v136, v136, v83
	v_sub_f32_e32 v137, v137, v83
	v_sub_f32_e32 v138, v138, v83
	v_sub_f32_e32 v139, v139, v83
	v_sub_f32_e32 v140, v140, v83
	v_sub_f32_e32 v141, v141, v83
	v_sub_f32_e32 v142, v142, v83
	v_sub_f32_e32 v143, v143, v83
	v_sub_f32_e32 v144, v144, v83
	v_sub_f32_e32 v145, v145, v83
	v_sub_f32_e32 v114, v114, v83
	v_sub_f32_e32 v115, v115, v83
	v_sub_f32_e32 v116, v116, v83
	v_sub_f32_e32 v117, v117, v83
	v_sub_f32_e32 v118, v118, v83
	v_sub_f32_e32 v119, v119, v83
	v_sub_f32_e32 v120, v120, v83
	v_sub_f32_e32 v121, v121, v83
	v_sub_f32_e32 v122, v122, v83
	v_sub_f32_e32 v123, v123, v83
	v_sub_f32_e32 v124, v124, v83
	v_sub_f32_e32 v125, v125, v83
	v_sub_f32_e32 v126, v126, v83
	v_sub_f32_e32 v127, v127, v83
	v_sub_f32_e32 v128, v128, v83
	v_sub_f32_e32 v129, v129, v83
	s_nop 1
	v_mul_f32_e32 v215, v215, v82
	s_branch .LBB0_1097
.LBB0_1107:
	v_max_f32_e32 v4, v4, v4
	v_max_f32_e32 v5, 0, v4
	v_exp_f32_e64 v4, -v5
	s_and_saveexec_b64 s[30:31], s[6:7]
	ds_write_b32 v244, v4
	s_or_b64 exec, exec, s[30:31]
	v_add_f32_e32 v246, v246, v5
	v_sub_f32_e32 v218, v218, v5
	v_sub_f32_e32 v219, v219, v5
	v_sub_f32_e32 v220, v220, v5
	v_sub_f32_e32 v221, v221, v5
	v_sub_f32_e32 v222, v222, v5
	v_sub_f32_e32 v223, v223, v5
	v_sub_f32_e32 v224, v224, v5
	v_sub_f32_e32 v225, v225, v5
	v_sub_f32_e32 v226, v226, v5
	v_sub_f32_e32 v227, v227, v5
	v_sub_f32_e32 v228, v228, v5
	v_sub_f32_e32 v229, v229, v5
	v_sub_f32_e32 v230, v230, v5
	v_sub_f32_e32 v231, v231, v5
	v_sub_f32_e32 v232, v232, v5
	v_sub_f32_e32 v233, v233, v5
	v_sub_f32_e32 v98, v98, v5
	v_sub_f32_e32 v99, v99, v5
	v_sub_f32_e32 v100, v100, v5
	v_sub_f32_e32 v101, v101, v5
	v_sub_f32_e32 v102, v102, v5
	v_sub_f32_e32 v103, v103, v5
	v_sub_f32_e32 v104, v104, v5
	v_sub_f32_e32 v105, v105, v5
	v_sub_f32_e32 v106, v106, v5
	v_sub_f32_e32 v107, v107, v5
	v_sub_f32_e32 v108, v108, v5
	v_sub_f32_e32 v109, v109, v5
	v_sub_f32_e32 v110, v110, v5
	v_sub_f32_e32 v111, v111, v5
	v_sub_f32_e32 v112, v112, v5
	v_sub_f32_e32 v113, v113, v5
	v_sub_f32_e32 v82, v82, v5
	v_sub_f32_e32 v83, v83, v5
	v_sub_f32_e32 v84, v84, v5
	v_sub_f32_e32 v85, v85, v5
	v_sub_f32_e32 v86, v86, v5
	v_sub_f32_e32 v87, v87, v5
	v_sub_f32_e32 v88, v88, v5
	v_sub_f32_e32 v89, v89, v5
	v_sub_f32_e32 v90, v90, v5
	v_sub_f32_e32 v91, v91, v5
	v_sub_f32_e32 v92, v92, v5
	v_sub_f32_e32 v93, v93, v5
	v_sub_f32_e32 v94, v94, v5
	v_sub_f32_e32 v95, v95, v5
	v_sub_f32_e32 v96, v96, v5
	v_sub_f32_e32 v97, v97, v5
	s_nop 1
	v_mul_f32_e32 v251, v251, v4
	s_branch .LBB0_1100
